# non-temporal hint also on the LayerNorm-epilogue residual loads (read once by their owner, no sharing)
# baseline (speedup 1.0000x reference)
.LBB0_1285:
	v_mov_b32_e32 v186, v177
	s_mov_b32 s8, s3
	v_mov_b32_e32 v187, v178
	s_mov_b32 s9, s72
	s_lshl_b32 s7, s14, 2
	s_ashr_i32 s10, s9, 1
	s_lshl_b32 s31, s8, 6
	s_add_i32 s38, s10, s7
	s_lshl_b32 s10, s40, 8
	s_lshl_b32 s6, s9, 5
	s_ashr_i32 s39, s38, 31
	s_add_i32 s79, s31, s10
	v_add_u32_e32 v128, s79, v186
	s_and_b32 s7, s6, 32
	s_lshl_b64 s[38:39], s[38:39], 22
	v_ashrrev_i32_e32 v129, 31, v128
	s_add_u32 s38, s58, s38
	v_lshlrev_b64 v[128:129], 7, v[128:129]
	s_addc_u32 s39, s59, s39
	v_lshlrev_b32_e32 v144, 3, v187
	v_lshl_add_u64 v[128:129], s[38:39], 0, v[128:129]
	s_lshl_b32 s12, s7, 1
	v_ashrrev_i32_e32 v145, 31, v144
	v_lshl_add_u64 v[128:129], v[128:129], 0, s[12:13]
	v_lshl_add_u64 v[132:133], v[144:145], 1, v[128:129]
	v_add_co_u32_e32 v128, vcc, s74, v132
	global_load_dwordx4 v[134:137], v[132:133], off nt
	global_load_dwordx4 v[138:141], v[132:133], off offset:2048 nt
	v_addc_co_u32_e32 v129, vcc, 0, v133, vcc
	v_add_co_u32_e32 v130, vcc, s51, v132
	global_load_dwordx4 v[146:149], v[128:129], off offset:-4096 nt
	s_nop 0
	v_addc_co_u32_e32 v131, vcc, 0, v133, vcc
	global_load_dwordx4 v[150:153], v[130:131], off offset:2048 nt
	v_add_co_u32_e32 v130, vcc, s73, v132
	s_lshl_b32 s7, s14, 8
	s_nop 0
	v_addc_co_u32_e32 v131, vcc, 0, v133, vcc
	global_load_dwordx4 v[154:157], v[130:131], off nt
	global_load_dwordx4 v[188:191], v[128:129], off nt
	global_load_dwordx4 v[192:195], v[130:131], off offset:2048 nt
	s_nop 0
	global_load_dwordx4 v[128:131], v[128:129], off offset:2048 nt
	s_add_i32 s6, s6, s7
	s_waitcnt vmcnt(0)
	v_lshlrev_b32_e32 v142, 16, v134
	v_and_b32_e32 v143, 0xffff0000, v134
	v_lshlrev_b32_e32 v134, 16, v135
	v_and_b32_e32 v135, 0xffff0000, v135
	v_lshlrev_b32_e32 v158, 16, v136
	v_and_b32_e32 v159, 0xffff0000, v136
	v_lshlrev_b32_e32 v136, 16, v137
	v_and_b32_e32 v137, 0xffff0000, v137
	v_lshlrev_b32_e32 v174, 16, v138
	v_and_b32_e32 v175, 0xffff0000, v138
	v_lshlrev_b32_e32 v138, 16, v139
	v_and_b32_e32 v139, 0xffff0000, v139
	v_lshlrev_b32_e32 v196, 16, v140
	v_and_b32_e32 v197, 0xffff0000, v140
	v_lshlrev_b32_e32 v140, 16, v141
	v_and_b32_e32 v141, 0xffff0000, v141
	v_pk_fma_f32 v[102:103], v[134:135], s[28:29], v[102:103] op_sel_hi:[1,0,1]
	v_pk_fma_f32 v[90:91], v[136:137], s[28:29], v[90:91] op_sel_hi:[1,0,1]
	v_lshlrev_b32_e32 v134, 16, v146
	v_and_b32_e32 v135, 0xffff0000, v146
	v_lshlrev_b32_e32 v136, 16, v147
	v_and_b32_e32 v137, 0xffff0000, v147
	v_pk_fma_f32 v[86:87], v[138:139], s[28:29], v[86:87] op_sel_hi:[1,0,1]
	v_pk_fma_f32 v[82:83], v[140:141], s[28:29], v[82:83] op_sel_hi:[1,0,1]
	v_lshlrev_b32_e32 v138, 16, v150
	v_and_b32_e32 v139, 0xffff0000, v150
	v_lshlrev_b32_e32 v140, 16, v151
	v_and_b32_e32 v141, 0xffff0000, v151
	v_pk_fma_f32 v[30:31], v[136:137], s[28:29], v[30:31] op_sel_hi:[1,0,1]
	v_pk_fma_f32 v[28:29], v[134:135], s[28:29], v[28:29] op_sel_hi:[1,0,1]
	v_lshlrev_b32_e32 v134, 16, v154
	v_and_b32_e32 v135, 0xffff0000, v154
	v_lshlrev_b32_e32 v136, 16, v155
	v_and_b32_e32 v137, 0xffff0000, v155
	v_pk_fma_f32 v[100:101], v[142:143], s[28:29], v[100:101] op_sel_hi:[1,0,1]
	v_lshlrev_b32_e32 v142, 16, v148
	v_and_b32_e32 v143, 0xffff0000, v148
	v_pk_fma_f32 v[6:7], v[140:141], s[28:29], v[6:7] op_sel_hi:[1,0,1]
	v_pk_fma_f32 v[4:5], v[138:139], s[28:29], v[4:5] op_sel_hi:[1,0,1]
	v_lshlrev_b32_e32 v138, 16, v156
	v_and_b32_e32 v139, 0xffff0000, v156
	v_lshlrev_b32_e32 v140, 16, v157
	v_and_b32_e32 v141, 0xffff0000, v157
	v_pk_fma_f32 v[98:99], v[136:137], s[28:29], v[98:99] op_sel_hi:[1,0,1]
	v_pk_fma_f32 v[96:97], v[134:135], s[28:29], v[96:97] op_sel_hi:[1,0,1]
	v_lshlrev_b32_e32 v134, 16, v188
	v_and_b32_e32 v135, 0xffff0000, v188
	v_lshlrev_b32_e32 v136, 16, v189
	v_and_b32_e32 v137, 0xffff0000, v189
	v_pk_fma_f32 v[16:17], v[142:143], s[28:29], v[16:17] op_sel_hi:[1,0,1]
	v_pk_fma_f32 v[94:95], v[140:141], s[28:29], v[94:95] op_sel_hi:[1,0,1]
	v_pk_fma_f32 v[92:93], v[138:139], s[28:29], v[92:93] op_sel_hi:[1,0,1]
	v_lshlrev_b32_e32 v138, 16, v190
	v_and_b32_e32 v139, 0xffff0000, v190
	v_lshlrev_b32_e32 v140, 16, v191
	v_and_b32_e32 v141, 0xffff0000, v191
	v_pk_fma_f32 v[14:15], v[136:137], s[28:29], v[14:15] op_sel_hi:[1,0,1]
	v_pk_fma_f32 v[12:13], v[134:135], s[28:29], v[12:13] op_sel_hi:[1,0,1]
	v_lshlrev_b32_e32 v134, 16, v192
	v_and_b32_e32 v135, 0xffff0000, v192
	v_lshlrev_b32_e32 v136, 16, v193
	v_and_b32_e32 v137, 0xffff0000, v193
	v_add_co_u32_e32 v142, vcc, s78, v132
	v_lshlrev_b32_e32 v146, 16, v149
	v_and_b32_e32 v147, 0xffff0000, v149
	v_lshlrev_b32_e32 v148, 16, v152
	v_and_b32_e32 v149, 0xffff0000, v152
	v_lshlrev_b32_e32 v150, 16, v153
	v_and_b32_e32 v151, 0xffff0000, v153
	v_pk_fma_f32 v[10:11], v[140:141], s[28:29], v[10:11] op_sel_hi:[1,0,1]
	v_pk_fma_f32 v[8:9], v[138:139], s[28:29], v[8:9] op_sel_hi:[1,0,1]
	v_lshlrev_b32_e32 v138, 16, v194
	v_and_b32_e32 v139, 0xffff0000, v194
	v_lshlrev_b32_e32 v140, 16, v195
	v_and_b32_e32 v141, 0xffff0000, v195
	v_pk_fma_f32 v[110:111], v[136:137], s[28:29], v[110:111] op_sel_hi:[1,0,1]
	v_pk_fma_f32 v[108:109], v[134:135], s[28:29], v[108:109] op_sel_hi:[1,0,1]
	v_lshlrev_b32_e32 v134, 16, v128
	v_and_b32_e32 v135, 0xffff0000, v128
	v_lshlrev_b32_e32 v128, 16, v129
	v_and_b32_e32 v129, 0xffff0000, v129
	v_lshlrev_b32_e32 v136, 16, v130
	v_and_b32_e32 v137, 0xffff0000, v130
	v_lshlrev_b32_e32 v130, 16, v131
	v_and_b32_e32 v131, 0xffff0000, v131
	v_addc_co_u32_e32 v143, vcc, 0, v133, vcc
	v_pk_fma_f32 v[88:89], v[158:159], s[28:29], v[88:89] op_sel_hi:[1,0,1]
	v_pk_fma_f32 v[84:85], v[174:175], s[28:29], v[84:85] op_sel_hi:[1,0,1]
	v_pk_fma_f32 v[80:81], v[196:197], s[28:29], v[80:81] op_sel_hi:[1,0,1]
	v_pk_fma_f32 v[18:19], v[146:147], s[28:29], v[18:19] op_sel_hi:[1,0,1]
	v_pk_fma_f32 v[2:3], v[150:151], s[28:29], v[2:3] op_sel_hi:[1,0,1]
	v_pk_fma_f32 v[0:1], v[148:149], s[28:29], v[0:1] op_sel_hi:[1,0,1]
	v_pk_fma_f32 v[106:107], v[140:141], s[28:29], v[106:107] op_sel_hi:[1,0,1]
	v_pk_fma_f32 v[104:105], v[138:139], s[28:29], v[104:105] op_sel_hi:[1,0,1]
	v_pk_fma_f32 v[26:27], v[128:129], s[28:29], v[26:27] op_sel_hi:[1,0,1]
	v_pk_fma_f32 v[24:25], v[134:135], s[28:29], v[24:25] op_sel_hi:[1,0,1]
	v_pk_fma_f32 v[22:23], v[130:131], s[28:29], v[22:23] op_sel_hi:[1,0,1]
	v_pk_fma_f32 v[20:21], v[136:137], s[28:29], v[20:21] op_sel_hi:[1,0,1]
	v_add_co_u32_e32 v158, vcc, s88, v132
	s_nop 1
	v_addc_co_u32_e32 v159, vcc, 0, v133, vcc
	global_load_dwordx4 v[128:131], v[142:143], off offset:-4096 nt
	v_add_co_u32_e32 v138, vcc, s55, v132
	global_load_dwordx4 v[134:137], v[158:159], off offset:-4096 nt
	s_nop 0
	v_addc_co_u32_e32 v139, vcc, 0, v133, vcc
	global_load_dwordx4 v[138:141], v[138:139], off offset:2048 nt
	v_add_co_u32_e32 v132, vcc, s75, v132
	v_pk_add_f32 v[174:175], v[102:103], v[90:91]
	s_nop 0
	v_addc_co_u32_e32 v133, vcc, 0, v133, vcc
	global_load_dwordx4 v[146:149], v[132:133], off offset:2048 nt
	global_load_dwordx4 v[150:153], v[142:143], off nt
	global_load_dwordx4 v[154:157], v[158:159], off nt
	global_load_dwordx4 v[188:191], v[142:143], off offset:2048 nt
	global_load_dwordx4 v[192:195], v[158:159], off offset:2048 nt
	v_cmp_eq_u32_e32 vcc, 0, v187
	s_waitcnt vmcnt(7)
	v_lshlrev_b32_e32 v132, 16, v128
	v_and_b32_e32 v133, 0xffff0000, v128
	v_lshlrev_b32_e32 v128, 16, v129
	v_and_b32_e32 v129, 0xffff0000, v129
	v_pk_fma_f32 v[118:119], v[128:129], s[28:29], v[118:119] op_sel_hi:[1,0,1]
	s_waitcnt vmcnt(6)
	v_lshlrev_b32_e32 v128, 16, v134
	v_and_b32_e32 v129, 0xffff0000, v134
	v_lshlrev_b32_e32 v142, 16, v130
	v_and_b32_e32 v143, 0xffff0000, v130
	v_lshlrev_b32_e32 v130, 16, v131
	v_and_b32_e32 v131, 0xffff0000, v131
	v_pk_fma_f32 v[116:117], v[132:133], s[28:29], v[116:117] op_sel_hi:[1,0,1]
	v_lshlrev_b32_e32 v132, 16, v136
	v_and_b32_e32 v133, 0xffff0000, v136
	v_pk_fma_f32 v[36:37], v[128:129], s[28:29], v[36:37] op_sel_hi:[1,0,1]
	s_waitcnt vmcnt(5)
	v_lshlrev_b32_e32 v128, 16, v138
	v_and_b32_e32 v129, 0xffff0000, v138
	v_pk_fma_f32 v[114:115], v[130:131], s[28:29], v[114:115] op_sel_hi:[1,0,1]
	v_lshlrev_b32_e32 v130, 16, v135
	v_and_b32_e32 v131, 0xffff0000, v135
	v_pk_fma_f32 v[32:33], v[132:133], s[28:29], v[32:33] op_sel_hi:[1,0,1]
	v_lshlrev_b32_e32 v132, 16, v140
	v_and_b32_e32 v133, 0xffff0000, v140
	v_pk_fma_f32 v[124:125], v[128:129], s[28:29], v[124:125] op_sel_hi:[1,0,1]
	s_waitcnt vmcnt(4)
	v_lshlrev_b32_e32 v128, 16, v146
	v_and_b32_e32 v129, 0xffff0000, v146
	v_lshlrev_b32_e32 v134, 16, v137
	v_and_b32_e32 v135, 0xffff0000, v137
	v_pk_fma_f32 v[38:39], v[130:131], s[28:29], v[38:39] op_sel_hi:[1,0,1]
	v_lshlrev_b32_e32 v130, 16, v139
	v_and_b32_e32 v131, 0xffff0000, v139
	v_pk_fma_f32 v[120:121], v[132:133], s[28:29], v[120:121] op_sel_hi:[1,0,1]
	v_lshlrev_b32_e32 v132, 16, v148
	v_and_b32_e32 v133, 0xffff0000, v148
	v_pk_fma_f32 v[44:45], v[128:129], s[28:29], v[44:45] op_sel_hi:[1,0,1]
	s_waitcnt vmcnt(3)
	v_lshlrev_b32_e32 v128, 16, v150
	v_and_b32_e32 v129, 0xffff0000, v150
	v_pk_fma_f32 v[34:35], v[134:135], s[28:29], v[34:35] op_sel_hi:[1,0,1]
	v_lshlrev_b32_e32 v134, 16, v141
	v_and_b32_e32 v135, 0xffff0000, v141
	v_pk_fma_f32 v[126:127], v[130:131], s[28:29], v[126:127] op_sel_hi:[1,0,1]
	v_lshlrev_b32_e32 v130, 16, v147
	v_and_b32_e32 v131, 0xffff0000, v147
	v_pk_fma_f32 v[40:41], v[132:133], s[28:29], v[40:41] op_sel_hi:[1,0,1]
	v_pk_fma_f32 v[132:133], v[128:129], s[28:29], v[76:77] op_sel_hi:[1,0,1]
	s_waitcnt vmcnt(2)
	v_lshlrev_b32_e32 v76, 16, v156
	v_and_b32_e32 v77, 0xffff0000, v156
	v_pk_fma_f32 v[122:123], v[134:135], s[28:29], v[122:123] op_sel_hi:[1,0,1]
	v_lshlrev_b32_e32 v134, 16, v149
	v_and_b32_e32 v135, 0xffff0000, v149
	v_pk_fma_f32 v[46:47], v[130:131], s[28:29], v[46:47] op_sel_hi:[1,0,1]
	v_lshlrev_b32_e32 v130, 16, v151
	v_and_b32_e32 v131, 0xffff0000, v151
	v_lshlrev_b32_e32 v136, 16, v152
	v_and_b32_e32 v137, 0xffff0000, v152
	v_lshlrev_b32_e32 v138, 16, v153
	v_and_b32_e32 v139, 0xffff0000, v153
	v_pk_fma_f32 v[48:49], v[76:77], s[28:29], v[48:49] op_sel_hi:[1,0,1]
	s_waitcnt vmcnt(1)
	v_lshlrev_b32_e32 v76, 16, v190
	v_and_b32_e32 v77, 0xffff0000, v190
	v_pk_fma_f32 v[42:43], v[134:135], s[28:29], v[42:43] op_sel_hi:[1,0,1]
	v_pk_fma_f32 v[134:135], v[130:131], s[28:29], v[78:79] op_sel_hi:[1,0,1]
	v_pk_fma_f32 v[130:131], v[138:139], s[28:29], v[74:75] op_sel_hi:[1,0,1]
	v_pk_fma_f32 v[128:129], v[136:137], s[28:29], v[72:73] op_sel_hi:[1,0,1]
	v_lshlrev_b32_e32 v72, 16, v154
	v_and_b32_e32 v73, 0xffff0000, v154
	v_lshlrev_b32_e32 v74, 16, v155
	v_and_b32_e32 v75, 0xffff0000, v155
	v_lshlrev_b32_e32 v78, 16, v157
	v_and_b32_e32 v79, 0xffff0000, v157
	v_pk_fma_f32 v[136:137], v[76:77], s[28:29], v[64:65] op_sel_hi:[1,0,1]
	s_waitcnt vmcnt(0)
	v_lshlrev_b32_e32 v64, 16, v192
	v_and_b32_e32 v65, 0xffff0000, v192
	v_pk_fma_f32 v[54:55], v[74:75], s[28:29], v[54:55] op_sel_hi:[1,0,1]
	v_pk_fma_f32 v[52:53], v[72:73], s[28:29], v[52:53] op_sel_hi:[1,0,1]
	v_pk_fma_f32 v[50:51], v[78:79], s[28:29], v[50:51] op_sel_hi:[1,0,1]
	v_lshlrev_b32_e32 v72, 16, v188
	v_and_b32_e32 v73, 0xffff0000, v188
	v_lshlrev_b32_e32 v74, 16, v189
	v_and_b32_e32 v75, 0xffff0000, v189
	v_lshlrev_b32_e32 v78, 16, v191
	v_and_b32_e32 v79, 0xffff0000, v191
	v_pk_fma_f32 v[60:61], v[64:65], s[28:29], v[60:61] op_sel_hi:[1,0,1]
	v_add_u32_e32 v64, s6, v144
	v_pk_fma_f32 v[112:113], v[142:143], s[28:29], v[112:113] op_sel_hi:[1,0,1]
	v_pk_fma_f32 v[142:143], v[74:75], s[28:29], v[70:71] op_sel_hi:[1,0,1]
	v_pk_fma_f32 v[140:141], v[72:73], s[28:29], v[68:69] op_sel_hi:[1,0,1]
	v_pk_fma_f32 v[138:139], v[78:79], s[28:29], v[66:67] op_sel_hi:[1,0,1]
	v_lshlrev_b32_e32 v66, 16, v193
	v_and_b32_e32 v67, 0xffff0000, v193
	v_lshlrev_b32_e32 v68, 16, v194
	v_and_b32_e32 v69, 0xffff0000, v194
	v_lshlrev_b32_e32 v70, 16, v195
	v_and_b32_e32 v71, 0xffff0000, v195
	v_ashrrev_i32_e32 v65, 31, v64
	v_pk_fma_f32 v[62:63], v[66:67], s[28:29], v[62:63] op_sel_hi:[1,0,1]
	v_pk_fma_f32 v[58:59], v[70:71], s[28:29], v[58:59] op_sel_hi:[1,0,1]
	v_pk_fma_f32 v[56:57], v[68:69], s[28:29], v[56:57] op_sel_hi:[1,0,1]
	v_lshlrev_b64 v[64:65], 2, v[64:65]
	v_lshl_add_u64 v[68:69], s[20:21], 0, v[64:65]
	v_lshl_add_u64 v[76:77], s[22:23], 0, v[64:65]
	global_load_dwordx4 v[144:147], v[68:69], off offset:16
	global_load_dwordx4 v[152:155], v[68:69], off
	global_load_dwordx4 v[148:151], v[76:77], off offset:16
	global_load_dwordx4 v[156:159], v[76:77], off
	global_load_dwordx4 v[64:67], v[68:69], off offset:528
	global_load_dwordx4 v[72:75], v[68:69], off offset:512
	s_nop 0
	global_load_dwordx4 v[68:71], v[76:77], off offset:528
	s_nop 0
	global_load_dwordx4 v[76:79], v[76:77], off offset:512
	v_pk_add_f32 v[188:189], v[100:101], v[88:89]
	v_pk_add_f32 v[190:191], v[30:31], v[18:19]
	v_pk_add_f32 v[192:193], v[28:29], v[16:17]
	v_pk_add_f32 v[174:175], v[174:175], v[190:191]
	v_pk_add_f32 v[188:189], v[188:189], v[192:193]
	v_add_f32_e32 v174, v174, v175
	v_add_f32_e32 v188, v188, v189
	v_add_f32_e32 v174, v188, v174
	v_mov_b32_e32 v175, v174
	s_nop 1
	v_permlane16_swap_b32_e32 v174, v175
	v_add_f32_e32 v174, v174, v175
	v_mov_b32_e32 v175, v174
	s_nop 1
	v_permlane32_swap_b32_e32 v174, v175
	v_add_f32_e32 v174, v174, v175
	v_fmamk_f32 v193, v174, 0xbc800000, v89
	v_fmamk_f32 v192, v174, 0xbc800000, v88
	v_fmamk_f32 v195, v174, 0xbc800000, v91
	v_fmamk_f32 v194, v174, 0xbc800000, v90
	v_fmamk_f32 v189, v174, 0xbc800000, v103
	v_fmamk_f32 v188, v174, 0xbc800000, v102
	v_fmamk_f32 v191, v174, 0xbc800000, v101
	v_fmamk_f32 v190, v174, 0xbc800000, v100
	v_fmamk_f32 v201, v174, 0xbc800000, v17
	v_fmamk_f32 v200, v174, 0xbc800000, v16
	v_fmamk_f32 v203, v174, 0xbc800000, v19
	v_fmamk_f32 v202, v174, 0xbc800000, v18
	v_pk_mul_f32 v[194:195], v[194:195], v[194:195]
	v_pk_mul_f32 v[192:193], v[192:193], v[192:193]
	v_fmamk_f32 v197, v174, 0xbc800000, v31
	v_fmamk_f32 v196, v174, 0xbc800000, v30
	v_fmamk_f32 v199, v174, 0xbc800000, v29
	v_fmamk_f32 v198, v174, 0xbc800000, v28
	v_pk_fma_f32 v[190:191], v[190:191], v[190:191], v[192:193]
	v_pk_fma_f32 v[188:189], v[188:189], v[188:189], v[194:195]
	v_pk_mul_f32 v[192:193], v[202:203], v[202:203]
	v_pk_mul_f32 v[194:195], v[200:201], v[200:201]
	v_pk_fma_f32 v[192:193], v[196:197], v[196:197], v[192:193]
	v_pk_fma_f32 v[194:195], v[198:199], v[198:199], v[194:195]
	v_pk_add_f32 v[188:189], v[188:189], v[192:193]
	v_pk_add_f32 v[190:191], v[190:191], v[194:195]
	v_add_f32_e32 v188, v188, v189
	v_add_f32_e32 v175, v190, v191
	v_add_f32_e32 v175, v175, v188
	v_mov_b32_e32 v188, v175
	s_nop 1
	v_permlane16_swap_b32_e32 v175, v188
	s_lshl_b32 s6, s9, 3
	v_add_f32_e32 v175, v175, v188
	s_add_i32 s11, s6, 0
	v_mov_b32_e32 v188, v175
	s_add_i32 s11, s11, 0x21000
	s_nop 0
	v_permlane32_swap_b32_e32 v175, v188
	s_and_saveexec_b64 s[6:7], vcc
	s_cbranch_execz .LBB0_1287
	s_lshl_b32 s15, s8, 11
	s_add_i32 s15, s11, s15
	v_mul_f32_e32 v174, 0x3c800000, v174
	v_add_f32_e32 v175, v175, v188
	v_lshl_add_u32 v188, v186, 5, s15
	ds_write_b64 v188, v[174:175]

.LBB0_1515:
	v_mov_b32_e32 v186, v177
	s_mov_b32 s8, s3
	v_mov_b32_e32 v187, v178
	s_mov_b32 s9, s72
	s_lshl_b32 s7, s14, 2
	s_ashr_i32 s10, s9, 1
	s_lshl_b32 s29, s8, 6
	s_add_i32 s38, s10, s7
	s_lshl_b32 s10, s40, 8
	s_lshl_b32 s6, s9, 5
	s_ashr_i32 s39, s38, 31
	s_add_i32 s31, s29, s10
	v_add_u32_e32 v128, s31, v186
	s_and_b32 s7, s6, 32
	s_lshl_b64 s[38:39], s[38:39], 22
	v_ashrrev_i32_e32 v129, 31, v128
	s_add_u32 s38, s58, s38
	v_lshlrev_b64 v[128:129], 7, v[128:129]
	s_addc_u32 s39, s59, s39
	v_lshlrev_b32_e32 v144, 3, v187
	v_lshl_add_u64 v[128:129], s[38:39], 0, v[128:129]
	s_lshl_b32 s12, s7, 1
	v_ashrrev_i32_e32 v145, 31, v144
	v_lshl_add_u64 v[128:129], v[128:129], 0, s[12:13]
	v_lshl_add_u64 v[132:133], v[144:145], 1, v[128:129]
	v_add_co_u32_e32 v128, vcc, s75, v132
	global_load_dwordx4 v[134:137], v[132:133], off nt
	global_load_dwordx4 v[138:141], v[132:133], off offset:2048 nt
	v_addc_co_u32_e32 v129, vcc, 0, v133, vcc
	v_add_co_u32_e32 v130, vcc, s73, v132
	global_load_dwordx4 v[146:149], v[128:129], off offset:-4096 nt
	s_nop 0
	v_addc_co_u32_e32 v131, vcc, 0, v133, vcc
	global_load_dwordx4 v[150:153], v[130:131], off offset:2048 nt
	v_add_co_u32_e32 v130, vcc, s74, v132
	s_lshl_b32 s7, s14, 8
	s_nop 0
	v_addc_co_u32_e32 v131, vcc, 0, v133, vcc
	global_load_dwordx4 v[154:157], v[130:131], off nt
	global_load_dwordx4 v[188:191], v[128:129], off nt
	global_load_dwordx4 v[192:195], v[130:131], off offset:2048 nt
	s_nop 0
	global_load_dwordx4 v[128:131], v[128:129], off offset:2048 nt
	s_add_i32 s6, s6, s7
	s_waitcnt vmcnt(0)
	v_lshlrev_b32_e32 v142, 16, v134
	v_and_b32_e32 v143, 0xffff0000, v134
	v_lshlrev_b32_e32 v134, 16, v135
	v_and_b32_e32 v135, 0xffff0000, v135
	v_lshlrev_b32_e32 v158, 16, v136
	v_and_b32_e32 v159, 0xffff0000, v136
	v_lshlrev_b32_e32 v136, 16, v137
	v_and_b32_e32 v137, 0xffff0000, v137
	v_lshlrev_b32_e32 v174, 16, v138
	v_and_b32_e32 v175, 0xffff0000, v138
	v_lshlrev_b32_e32 v138, 16, v139
	v_and_b32_e32 v139, 0xffff0000, v139
	v_lshlrev_b32_e32 v196, 16, v140
	v_and_b32_e32 v197, 0xffff0000, v140
	v_lshlrev_b32_e32 v140, 16, v141
	v_and_b32_e32 v141, 0xffff0000, v141
	v_pk_fma_f32 v[102:103], v[134:135], s[26:27], v[102:103] op_sel_hi:[1,0,1]
	v_pk_fma_f32 v[90:91], v[136:137], s[26:27], v[90:91] op_sel_hi:[1,0,1]
	v_lshlrev_b32_e32 v134, 16, v146
	v_and_b32_e32 v135, 0xffff0000, v146
	v_lshlrev_b32_e32 v136, 16, v147
	v_and_b32_e32 v137, 0xffff0000, v147
	v_pk_fma_f32 v[86:87], v[138:139], s[26:27], v[86:87] op_sel_hi:[1,0,1]
	v_pk_fma_f32 v[82:83], v[140:141], s[26:27], v[82:83] op_sel_hi:[1,0,1]
	v_lshlrev_b32_e32 v138, 16, v150
	v_and_b32_e32 v139, 0xffff0000, v150
	v_lshlrev_b32_e32 v140, 16, v151
	v_and_b32_e32 v141, 0xffff0000, v151
	v_pk_fma_f32 v[30:31], v[136:137], s[26:27], v[30:31] op_sel_hi:[1,0,1]
	v_pk_fma_f32 v[28:29], v[134:135], s[26:27], v[28:29] op_sel_hi:[1,0,1]
	v_lshlrev_b32_e32 v134, 16, v154
	v_and_b32_e32 v135, 0xffff0000, v154
	v_lshlrev_b32_e32 v136, 16, v155
	v_and_b32_e32 v137, 0xffff0000, v155
	v_pk_fma_f32 v[100:101], v[142:143], s[26:27], v[100:101] op_sel_hi:[1,0,1]
	v_lshlrev_b32_e32 v142, 16, v148
	v_and_b32_e32 v143, 0xffff0000, v148
	v_pk_fma_f32 v[6:7], v[140:141], s[26:27], v[6:7] op_sel_hi:[1,0,1]
	v_pk_fma_f32 v[4:5], v[138:139], s[26:27], v[4:5] op_sel_hi:[1,0,1]
	v_lshlrev_b32_e32 v138, 16, v156
	v_and_b32_e32 v139, 0xffff0000, v156
	v_lshlrev_b32_e32 v140, 16, v157
	v_and_b32_e32 v141, 0xffff0000, v157
	v_pk_fma_f32 v[98:99], v[136:137], s[26:27], v[98:99] op_sel_hi:[1,0,1]
	v_pk_fma_f32 v[96:97], v[134:135], s[26:27], v[96:97] op_sel_hi:[1,0,1]
	v_lshlrev_b32_e32 v134, 16, v188
	v_and_b32_e32 v135, 0xffff0000, v188
	v_lshlrev_b32_e32 v136, 16, v189
	v_and_b32_e32 v137, 0xffff0000, v189
	v_pk_fma_f32 v[16:17], v[142:143], s[26:27], v[16:17] op_sel_hi:[1,0,1]
	v_pk_fma_f32 v[94:95], v[140:141], s[26:27], v[94:95] op_sel_hi:[1,0,1]
	v_pk_fma_f32 v[92:93], v[138:139], s[26:27], v[92:93] op_sel_hi:[1,0,1]
	v_lshlrev_b32_e32 v138, 16, v190
	v_and_b32_e32 v139, 0xffff0000, v190
	v_lshlrev_b32_e32 v140, 16, v191
	v_and_b32_e32 v141, 0xffff0000, v191
	v_pk_fma_f32 v[14:15], v[136:137], s[26:27], v[14:15] op_sel_hi:[1,0,1]
	v_pk_fma_f32 v[12:13], v[134:135], s[26:27], v[12:13] op_sel_hi:[1,0,1]
	v_lshlrev_b32_e32 v134, 16, v192
	v_and_b32_e32 v135, 0xffff0000, v192
	v_lshlrev_b32_e32 v136, 16, v193
	v_and_b32_e32 v137, 0xffff0000, v193
	v_add_co_u32_e32 v142, vcc, s88, v132
	v_lshlrev_b32_e32 v146, 16, v149
	v_and_b32_e32 v147, 0xffff0000, v149
	v_lshlrev_b32_e32 v148, 16, v152
	v_and_b32_e32 v149, 0xffff0000, v152
	v_lshlrev_b32_e32 v150, 16, v153
	v_and_b32_e32 v151, 0xffff0000, v153
	v_pk_fma_f32 v[10:11], v[140:141], s[26:27], v[10:11] op_sel_hi:[1,0,1]
	v_pk_fma_f32 v[8:9], v[138:139], s[26:27], v[8:9] op_sel_hi:[1,0,1]
	v_lshlrev_b32_e32 v138, 16, v194
	v_and_b32_e32 v139, 0xffff0000, v194
	v_lshlrev_b32_e32 v140, 16, v195
	v_and_b32_e32 v141, 0xffff0000, v195
	v_pk_fma_f32 v[110:111], v[136:137], s[26:27], v[110:111] op_sel_hi:[1,0,1]
	v_pk_fma_f32 v[108:109], v[134:135], s[26:27], v[108:109] op_sel_hi:[1,0,1]
	v_lshlrev_b32_e32 v134, 16, v128
	v_and_b32_e32 v135, 0xffff0000, v128
	v_lshlrev_b32_e32 v128, 16, v129
	v_and_b32_e32 v129, 0xffff0000, v129
	v_lshlrev_b32_e32 v136, 16, v130
	v_and_b32_e32 v137, 0xffff0000, v130
	v_lshlrev_b32_e32 v130, 16, v131
	v_and_b32_e32 v131, 0xffff0000, v131
	v_addc_co_u32_e32 v143, vcc, 0, v133, vcc
	v_pk_fma_f32 v[88:89], v[158:159], s[26:27], v[88:89] op_sel_hi:[1,0,1]
	v_pk_fma_f32 v[84:85], v[174:175], s[26:27], v[84:85] op_sel_hi:[1,0,1]
	v_pk_fma_f32 v[80:81], v[196:197], s[26:27], v[80:81] op_sel_hi:[1,0,1]
	v_pk_fma_f32 v[18:19], v[146:147], s[26:27], v[18:19] op_sel_hi:[1,0,1]
	v_pk_fma_f32 v[2:3], v[150:151], s[26:27], v[2:3] op_sel_hi:[1,0,1]
	v_pk_fma_f32 v[0:1], v[148:149], s[26:27], v[0:1] op_sel_hi:[1,0,1]
	v_pk_fma_f32 v[106:107], v[140:141], s[26:27], v[106:107] op_sel_hi:[1,0,1]
	v_pk_fma_f32 v[104:105], v[138:139], s[26:27], v[104:105] op_sel_hi:[1,0,1]
	v_pk_fma_f32 v[26:27], v[128:129], s[26:27], v[26:27] op_sel_hi:[1,0,1]
	v_pk_fma_f32 v[24:25], v[134:135], s[26:27], v[24:25] op_sel_hi:[1,0,1]
	v_pk_fma_f32 v[22:23], v[130:131], s[26:27], v[22:23] op_sel_hi:[1,0,1]
	v_pk_fma_f32 v[20:21], v[136:137], s[26:27], v[20:21] op_sel_hi:[1,0,1]
	v_add_co_u32_e32 v158, vcc, s96, v132
	s_nop 1
	v_addc_co_u32_e32 v159, vcc, 0, v133, vcc
	global_load_dwordx4 v[128:131], v[142:143], off offset:-4096 nt
	v_add_co_u32_e32 v138, vcc, s2, v132
	global_load_dwordx4 v[134:137], v[158:159], off offset:-4096 nt
	s_nop 0
	v_addc_co_u32_e32 v139, vcc, 0, v133, vcc
	global_load_dwordx4 v[138:141], v[138:139], off offset:2048 nt
	v_add_co_u32_e32 v132, vcc, s78, v132
	v_pk_add_f32 v[174:175], v[102:103], v[90:91]
	s_nop 0
	v_addc_co_u32_e32 v133, vcc, 0, v133, vcc
	global_load_dwordx4 v[146:149], v[132:133], off offset:2048 nt
	global_load_dwordx4 v[150:153], v[142:143], off nt
	global_load_dwordx4 v[154:157], v[158:159], off nt
	global_load_dwordx4 v[188:191], v[142:143], off offset:2048 nt
	global_load_dwordx4 v[192:195], v[158:159], off offset:2048 nt
	v_cmp_eq_u32_e32 vcc, 0, v187
	s_waitcnt vmcnt(7)
	v_lshlrev_b32_e32 v132, 16, v128
	v_and_b32_e32 v133, 0xffff0000, v128
	v_lshlrev_b32_e32 v128, 16, v129
	v_and_b32_e32 v129, 0xffff0000, v129
	v_pk_fma_f32 v[118:119], v[128:129], s[26:27], v[118:119] op_sel_hi:[1,0,1]
	s_waitcnt vmcnt(6)
	v_lshlrev_b32_e32 v128, 16, v134
	v_and_b32_e32 v129, 0xffff0000, v134
	v_lshlrev_b32_e32 v142, 16, v130
	v_and_b32_e32 v143, 0xffff0000, v130
	v_lshlrev_b32_e32 v130, 16, v131
	v_and_b32_e32 v131, 0xffff0000, v131
	v_pk_fma_f32 v[116:117], v[132:133], s[26:27], v[116:117] op_sel_hi:[1,0,1]
	v_lshlrev_b32_e32 v132, 16, v136
	v_and_b32_e32 v133, 0xffff0000, v136
	v_pk_fma_f32 v[36:37], v[128:129], s[26:27], v[36:37] op_sel_hi:[1,0,1]
	s_waitcnt vmcnt(5)
	v_lshlrev_b32_e32 v128, 16, v138
	v_and_b32_e32 v129, 0xffff0000, v138
	v_pk_fma_f32 v[114:115], v[130:131], s[26:27], v[114:115] op_sel_hi:[1,0,1]
	v_lshlrev_b32_e32 v130, 16, v135
	v_and_b32_e32 v131, 0xffff0000, v135
	v_pk_fma_f32 v[32:33], v[132:133], s[26:27], v[32:33] op_sel_hi:[1,0,1]
	v_lshlrev_b32_e32 v132, 16, v140
	v_and_b32_e32 v133, 0xffff0000, v140
	v_pk_fma_f32 v[124:125], v[128:129], s[26:27], v[124:125] op_sel_hi:[1,0,1]
	s_waitcnt vmcnt(4)
	v_lshlrev_b32_e32 v128, 16, v146
	v_and_b32_e32 v129, 0xffff0000, v146
	v_lshlrev_b32_e32 v134, 16, v137
	v_and_b32_e32 v135, 0xffff0000, v137
	v_pk_fma_f32 v[38:39], v[130:131], s[26:27], v[38:39] op_sel_hi:[1,0,1]
	v_lshlrev_b32_e32 v130, 16, v139
	v_and_b32_e32 v131, 0xffff0000, v139
	v_pk_fma_f32 v[120:121], v[132:133], s[26:27], v[120:121] op_sel_hi:[1,0,1]
	v_lshlrev_b32_e32 v132, 16, v148
	v_and_b32_e32 v133, 0xffff0000, v148
	v_pk_fma_f32 v[44:45], v[128:129], s[26:27], v[44:45] op_sel_hi:[1,0,1]
	s_waitcnt vmcnt(3)
	v_lshlrev_b32_e32 v128, 16, v150
	v_and_b32_e32 v129, 0xffff0000, v150
	v_pk_fma_f32 v[34:35], v[134:135], s[26:27], v[34:35] op_sel_hi:[1,0,1]
	v_lshlrev_b32_e32 v134, 16, v141
	v_and_b32_e32 v135, 0xffff0000, v141
	v_pk_fma_f32 v[126:127], v[130:131], s[26:27], v[126:127] op_sel_hi:[1,0,1]
	v_lshlrev_b32_e32 v130, 16, v147
	v_and_b32_e32 v131, 0xffff0000, v147
	v_pk_fma_f32 v[40:41], v[132:133], s[26:27], v[40:41] op_sel_hi:[1,0,1]
	v_pk_fma_f32 v[132:133], v[128:129], s[26:27], v[76:77] op_sel_hi:[1,0,1]
	s_waitcnt vmcnt(2)
	v_lshlrev_b32_e32 v76, 16, v156
	v_and_b32_e32 v77, 0xffff0000, v156
	v_pk_fma_f32 v[122:123], v[134:135], s[26:27], v[122:123] op_sel_hi:[1,0,1]
	v_lshlrev_b32_e32 v134, 16, v149
	v_and_b32_e32 v135, 0xffff0000, v149
	v_pk_fma_f32 v[46:47], v[130:131], s[26:27], v[46:47] op_sel_hi:[1,0,1]
	v_lshlrev_b32_e32 v130, 16, v151
	v_and_b32_e32 v131, 0xffff0000, v151
	v_lshlrev_b32_e32 v136, 16, v152
	v_and_b32_e32 v137, 0xffff0000, v152
	v_lshlrev_b32_e32 v138, 16, v153
	v_and_b32_e32 v139, 0xffff0000, v153
	v_pk_fma_f32 v[48:49], v[76:77], s[26:27], v[48:49] op_sel_hi:[1,0,1]
	s_waitcnt vmcnt(1)
	v_lshlrev_b32_e32 v76, 16, v190
	v_and_b32_e32 v77, 0xffff0000, v190
	v_pk_fma_f32 v[42:43], v[134:135], s[26:27], v[42:43] op_sel_hi:[1,0,1]
	v_pk_fma_f32 v[134:135], v[130:131], s[26:27], v[78:79] op_sel_hi:[1,0,1]
	v_pk_fma_f32 v[130:131], v[138:139], s[26:27], v[74:75] op_sel_hi:[1,0,1]
	v_pk_fma_f32 v[128:129], v[136:137], s[26:27], v[72:73] op_sel_hi:[1,0,1]
	v_lshlrev_b32_e32 v72, 16, v154
	v_and_b32_e32 v73, 0xffff0000, v154
	v_lshlrev_b32_e32 v74, 16, v155
	v_and_b32_e32 v75, 0xffff0000, v155
	v_lshlrev_b32_e32 v78, 16, v157
	v_and_b32_e32 v79, 0xffff0000, v157
	v_pk_fma_f32 v[136:137], v[76:77], s[26:27], v[64:65] op_sel_hi:[1,0,1]
	s_waitcnt vmcnt(0)
	v_lshlrev_b32_e32 v64, 16, v192
	v_and_b32_e32 v65, 0xffff0000, v192
	v_pk_fma_f32 v[54:55], v[74:75], s[26:27], v[54:55] op_sel_hi:[1,0,1]
	v_pk_fma_f32 v[52:53], v[72:73], s[26:27], v[52:53] op_sel_hi:[1,0,1]
	v_pk_fma_f32 v[50:51], v[78:79], s[26:27], v[50:51] op_sel_hi:[1,0,1]
	v_lshlrev_b32_e32 v72, 16, v188
	v_and_b32_e32 v73, 0xffff0000, v188
	v_lshlrev_b32_e32 v74, 16, v189
	v_and_b32_e32 v75, 0xffff0000, v189
	v_lshlrev_b32_e32 v78, 16, v191
	v_and_b32_e32 v79, 0xffff0000, v191
	v_pk_fma_f32 v[60:61], v[64:65], s[26:27], v[60:61] op_sel_hi:[1,0,1]
	v_add_u32_e32 v64, s6, v144
	v_pk_fma_f32 v[112:113], v[142:143], s[26:27], v[112:113] op_sel_hi:[1,0,1]
	v_pk_fma_f32 v[142:143], v[74:75], s[26:27], v[70:71] op_sel_hi:[1,0,1]
	v_pk_fma_f32 v[140:141], v[72:73], s[26:27], v[68:69] op_sel_hi:[1,0,1]
	v_pk_fma_f32 v[138:139], v[78:79], s[26:27], v[66:67] op_sel_hi:[1,0,1]
	v_lshlrev_b32_e32 v66, 16, v193
	v_and_b32_e32 v67, 0xffff0000, v193
	v_lshlrev_b32_e32 v68, 16, v194
	v_and_b32_e32 v69, 0xffff0000, v194
	v_lshlrev_b32_e32 v70, 16, v195
	v_and_b32_e32 v71, 0xffff0000, v195
	v_ashrrev_i32_e32 v65, 31, v64
	v_pk_fma_f32 v[62:63], v[66:67], s[26:27], v[62:63] op_sel_hi:[1,0,1]
	v_pk_fma_f32 v[58:59], v[70:71], s[26:27], v[58:59] op_sel_hi:[1,0,1]
	v_pk_fma_f32 v[56:57], v[68:69], s[26:27], v[56:57] op_sel_hi:[1,0,1]
	v_lshlrev_b64 v[64:65], 2, v[64:65]
	v_lshl_add_u64 v[68:69], s[18:19], 0, v[64:65]
	v_lshl_add_u64 v[76:77], s[20:21], 0, v[64:65]
	global_load_dwordx4 v[144:147], v[68:69], off offset:16
	global_load_dwordx4 v[152:155], v[68:69], off
	global_load_dwordx4 v[148:151], v[76:77], off offset:16
	global_load_dwordx4 v[156:159], v[76:77], off
	global_load_dwordx4 v[64:67], v[68:69], off offset:528
	global_load_dwordx4 v[72:75], v[68:69], off offset:512
	s_nop 0
	global_load_dwordx4 v[68:71], v[76:77], off offset:528
	s_nop 0
	global_load_dwordx4 v[76:79], v[76:77], off offset:512
	v_pk_add_f32 v[188:189], v[100:101], v[88:89]
	v_pk_add_f32 v[190:191], v[30:31], v[18:19]
	v_pk_add_f32 v[192:193], v[28:29], v[16:17]
	v_pk_add_f32 v[174:175], v[174:175], v[190:191]
	v_pk_add_f32 v[188:189], v[188:189], v[192:193]
	v_add_f32_e32 v174, v174, v175
	v_add_f32_e32 v188, v188, v189
	v_add_f32_e32 v174, v188, v174
	v_mov_b32_e32 v175, v174
	s_nop 1
	v_permlane16_swap_b32_e32 v174, v175
	v_add_f32_e32 v174, v174, v175
	v_mov_b32_e32 v175, v174
	s_nop 1
	v_permlane32_swap_b32_e32 v174, v175
	v_add_f32_e32 v174, v174, v175
	v_fmamk_f32 v193, v174, 0xbc800000, v89
	v_fmamk_f32 v192, v174, 0xbc800000, v88
	v_fmamk_f32 v195, v174, 0xbc800000, v91
	v_fmamk_f32 v194, v174, 0xbc800000, v90
	v_fmamk_f32 v189, v174, 0xbc800000, v103
	v_fmamk_f32 v188, v174, 0xbc800000, v102
	v_fmamk_f32 v191, v174, 0xbc800000, v101
	v_fmamk_f32 v190, v174, 0xbc800000, v100
	v_fmamk_f32 v201, v174, 0xbc800000, v17
	v_fmamk_f32 v200, v174, 0xbc800000, v16
	v_fmamk_f32 v203, v174, 0xbc800000, v19
	v_fmamk_f32 v202, v174, 0xbc800000, v18
	v_pk_mul_f32 v[194:195], v[194:195], v[194:195]
	v_pk_mul_f32 v[192:193], v[192:193], v[192:193]
	v_fmamk_f32 v197, v174, 0xbc800000, v31
	v_fmamk_f32 v196, v174, 0xbc800000, v30
	v_fmamk_f32 v199, v174, 0xbc800000, v29
	v_fmamk_f32 v198, v174, 0xbc800000, v28
	v_pk_fma_f32 v[190:191], v[190:191], v[190:191], v[192:193]
	v_pk_fma_f32 v[188:189], v[188:189], v[188:189], v[194:195]
	v_pk_mul_f32 v[192:193], v[202:203], v[202:203]
	v_pk_mul_f32 v[194:195], v[200:201], v[200:201]
	v_pk_fma_f32 v[192:193], v[196:197], v[196:197], v[192:193]
	v_pk_fma_f32 v[194:195], v[198:199], v[198:199], v[194:195]
	v_pk_add_f32 v[188:189], v[188:189], v[192:193]
	v_pk_add_f32 v[190:191], v[190:191], v[194:195]
	v_add_f32_e32 v188, v188, v189
	v_add_f32_e32 v175, v190, v191
	v_add_f32_e32 v175, v175, v188
	v_mov_b32_e32 v188, v175
	s_nop 1
	v_permlane16_swap_b32_e32 v175, v188
	s_lshl_b32 s6, s9, 3
	v_add_f32_e32 v175, v175, v188
	s_add_i32 s11, s6, 0
	v_mov_b32_e32 v188, v175
	s_add_i32 s11, s11, 0x21000
	s_nop 0
	v_permlane32_swap_b32_e32 v175, v188
	s_and_saveexec_b64 s[6:7], vcc
	s_cbranch_execz .LBB0_1517
	s_lshl_b32 s15, s8, 11
	s_add_i32 s15, s11, s15
	v_mul_f32_e32 v174, 0x3c800000, v174
	v_add_f32_e32 v175, v175, v188
	v_lshl_add_u32 v188, v186, 5, s15
	ds_write_b64 v188, v[174:175]

.LBB0_1709:
	v_mov_b32_e32 v187, v178
	s_mov_b32 s8, s4
	v_mov_b32_e32 v186, v177
	s_mov_b32 s9, s55
	s_lshl_b32 s7, s14, 2
	s_ashr_i32 s10, s8, 1
	s_lshl_b32 s31, s9, 6
	s_add_i32 s38, s10, s7
	s_lshl_b32 s10, s40, 8
	s_lshl_b32 s6, s8, 5
	s_ashr_i32 s39, s38, 31
	s_add_i32 s51, s31, s10
	v_add_u32_e32 v128, s51, v186
	s_and_b32 s7, s6, 32
	s_lshl_b64 s[38:39], s[38:39], 22
	v_ashrrev_i32_e32 v129, 31, v128
	s_add_u32 s38, s58, s38
	v_lshlrev_b64 v[128:129], 7, v[128:129]
	s_addc_u32 s39, s59, s39
	v_lshlrev_b32_e32 v148, 3, v187
	v_lshl_add_u64 v[128:129], s[38:39], 0, v[128:129]
	s_lshl_b32 s12, s7, 1
	v_ashrrev_i32_e32 v149, 31, v148
	v_lshl_add_u64 v[128:129], v[128:129], 0, s[12:13]
	v_lshl_add_u64 v[128:129], v[148:149], 1, v[128:129]
	v_add_co_u32_e32 v146, vcc, s69, v128
	global_load_dwordx4 v[130:133], v[128:129], off nt
	global_load_dwordx4 v[134:137], v[128:129], off offset:2048 nt
	v_addc_co_u32_e32 v147, vcc, 0, v129, vcc
	v_add_co_u32_e32 v142, vcc, s33, v128
	global_load_dwordx4 v[138:141], v[146:147], off offset:-4096 nt
	s_nop 0
	v_addc_co_u32_e32 v143, vcc, 0, v129, vcc
	global_load_dwordx4 v[142:145], v[142:143], off offset:2048 nt
	v_add_co_u32_e32 v158, vcc, s56, v128
	global_load_dwordx4 v[154:157], v[146:147], off nt
	s_nop 0
	v_addc_co_u32_e32 v159, vcc, 0, v129, vcc
	global_load_dwordx4 v[150:153], v[158:159], off nt
	global_load_dwordx4 v[188:191], v[158:159], off offset:2048 nt
	global_load_dwordx4 v[192:195], v[146:147], off offset:2048 nt
	v_pk_mul_f32 v[90:91], v[90:91], 0.5 op_sel_hi:[1,0]
	v_pk_mul_f32 v[88:89], v[88:89], 0.5 op_sel_hi:[1,0]
	v_pk_mul_f32 v[174:175], v[86:87], 0.5 op_sel_hi:[1,0]
	v_pk_mul_f32 v[196:197], v[84:85], 0.5 op_sel_hi:[1,0]
	v_pk_mul_f32 v[198:199], v[82:83], 0.5 op_sel_hi:[1,0]
	v_pk_mul_f32 v[200:201], v[80:81], 0.5 op_sel_hi:[1,0]
	v_pk_mul_f32 v[14:15], v[14:15], 0.5 op_sel_hi:[1,0]
	v_pk_mul_f32 v[12:13], v[12:13], 0.5 op_sel_hi:[1,0]
	v_pk_mul_f32 v[94:95], v[94:95], 0.5 op_sel_hi:[1,0]
	v_pk_mul_f32 v[92:93], v[92:93], 0.5 op_sel_hi:[1,0]
	v_pk_mul_f32 v[10:11], v[10:11], 0.5 op_sel_hi:[1,0]
	v_pk_mul_f32 v[8:9], v[8:9], 0.5 op_sel_hi:[1,0]
	s_lshl_b32 s7, s14, 8
	s_add_i32 s6, s6, s7
	s_waitcnt vmcnt(0)
	v_lshlrev_b32_e32 v80, 16, v130
	v_and_b32_e32 v81, 0xffff0000, v130
	v_lshlrev_b32_e32 v82, 16, v131
	v_and_b32_e32 v83, 0xffff0000, v131
	v_lshlrev_b32_e32 v84, 16, v132
	v_and_b32_e32 v85, 0xffff0000, v132
	v_lshlrev_b32_e32 v86, 16, v133
	v_and_b32_e32 v87, 0xffff0000, v133
	v_lshlrev_b32_e32 v130, 16, v134
	v_and_b32_e32 v131, 0xffff0000, v134
	v_lshlrev_b32_e32 v132, 16, v135
	v_and_b32_e32 v133, 0xffff0000, v135
	v_lshlrev_b32_e32 v134, 16, v136
	v_and_b32_e32 v135, 0xffff0000, v136
	v_lshlrev_b32_e32 v136, 16, v137
	v_and_b32_e32 v137, 0xffff0000, v137
	v_pk_fma_f32 v[90:91], v[86:87], s[28:29], v[90:91] op_sel_hi:[1,0,1]
	v_pk_fma_f32 v[88:89], v[84:85], s[28:29], v[88:89] op_sel_hi:[1,0,1]
	v_pk_fma_f32 v[86:87], v[132:133], s[28:29], v[14:15] op_sel_hi:[1,0,1]
	v_pk_fma_f32 v[84:85], v[130:131], s[28:29], v[12:13] op_sel_hi:[1,0,1]
	v_lshlrev_b32_e32 v130, 16, v142
	v_and_b32_e32 v131, 0xffff0000, v142
	v_lshlrev_b32_e32 v132, 16, v143
	v_and_b32_e32 v133, 0xffff0000, v143
	v_pk_fma_f32 v[94:95], v[82:83], s[28:29], v[94:95] op_sel_hi:[1,0,1]
	v_pk_fma_f32 v[92:93], v[80:81], s[28:29], v[92:93] op_sel_hi:[1,0,1]
	v_pk_fma_f32 v[82:83], v[136:137], s[28:29], v[10:11] op_sel_hi:[1,0,1]
	v_pk_fma_f32 v[80:81], v[134:135], s[28:29], v[8:9] op_sel_hi:[1,0,1]
	v_lshlrev_b32_e32 v134, 16, v144
	v_and_b32_e32 v135, 0xffff0000, v144
	v_lshlrev_b32_e32 v136, 16, v145
	v_and_b32_e32 v137, 0xffff0000, v145
	v_pk_mul_f32 v[130:131], v[130:131], s[28:29] op_sel_hi:[1,0]
	v_pk_mul_f32 v[132:133], v[132:133], s[28:29] op_sel_hi:[1,0]
	v_pk_fma_f32 v[4:5], v[4:5], 0.5, v[130:131] op_sel_hi:[1,0,1]
	v_pk_fma_f32 v[6:7], v[6:7], 0.5, v[132:133] op_sel_hi:[1,0,1]
	v_pk_mul_f32 v[130:131], v[134:135], s[28:29] op_sel_hi:[1,0]
	v_pk_mul_f32 v[132:133], v[136:137], s[28:29] op_sel_hi:[1,0]
	v_pk_fma_f32 v[0:1], v[0:1], 0.5, v[130:131] op_sel_hi:[1,0,1]
	v_pk_fma_f32 v[2:3], v[2:3], 0.5, v[132:133] op_sel_hi:[1,0,1]
	v_lshlrev_b32_e32 v130, 16, v150
	v_and_b32_e32 v131, 0xffff0000, v150
	v_lshlrev_b32_e32 v132, 16, v151
	v_and_b32_e32 v133, 0xffff0000, v151
	v_lshlrev_b32_e32 v134, 16, v152
	v_and_b32_e32 v135, 0xffff0000, v152
	v_lshlrev_b32_e32 v136, 16, v153
	v_and_b32_e32 v137, 0xffff0000, v153
	v_pk_mul_f32 v[130:131], v[130:131], s[28:29] op_sel_hi:[1,0]
	v_pk_mul_f32 v[132:133], v[132:133], s[28:29] op_sel_hi:[1,0]
	v_pk_fma_f32 v[100:101], v[100:101], 0.5, v[130:131] op_sel_hi:[1,0,1]
	v_pk_fma_f32 v[102:103], v[102:103], 0.5, v[132:133] op_sel_hi:[1,0,1]
	v_pk_mul_f32 v[130:131], v[134:135], s[28:29] op_sel_hi:[1,0]
	v_pk_mul_f32 v[132:133], v[136:137], s[28:29] op_sel_hi:[1,0]
	v_pk_fma_f32 v[96:97], v[96:97], 0.5, v[130:131] op_sel_hi:[1,0,1]
	v_pk_fma_f32 v[98:99], v[98:99], 0.5, v[132:133] op_sel_hi:[1,0,1]
	v_lshlrev_b32_e32 v130, 16, v154
	v_and_b32_e32 v131, 0xffff0000, v154
	v_lshlrev_b32_e32 v132, 16, v155
	v_and_b32_e32 v133, 0xffff0000, v155
	v_lshlrev_b32_e32 v134, 16, v156
	v_and_b32_e32 v135, 0xffff0000, v156
	v_lshlrev_b32_e32 v136, 16, v157
	v_and_b32_e32 v137, 0xffff0000, v157
	v_pk_mul_f32 v[130:131], v[130:131], s[28:29] op_sel_hi:[1,0]
	v_pk_mul_f32 v[132:133], v[132:133], s[28:29] op_sel_hi:[1,0]
	v_pk_fma_f32 v[20:21], v[20:21], 0.5, v[130:131] op_sel_hi:[1,0,1]
	v_pk_fma_f32 v[22:23], v[22:23], 0.5, v[132:133] op_sel_hi:[1,0,1]
	v_pk_mul_f32 v[130:131], v[134:135], s[28:29] op_sel_hi:[1,0]
	v_pk_mul_f32 v[132:133], v[136:137], s[28:29] op_sel_hi:[1,0]
	v_pk_fma_f32 v[16:17], v[16:17], 0.5, v[130:131] op_sel_hi:[1,0,1]
	v_pk_fma_f32 v[18:19], v[18:19], 0.5, v[132:133] op_sel_hi:[1,0,1]
	v_lshlrev_b32_e32 v130, 16, v188
	v_and_b32_e32 v131, 0xffff0000, v188
	v_lshlrev_b32_e32 v132, 16, v189
	v_and_b32_e32 v133, 0xffff0000, v189
	v_lshlrev_b32_e32 v134, 16, v190
	v_and_b32_e32 v135, 0xffff0000, v190
	v_lshlrev_b32_e32 v136, 16, v191
	v_and_b32_e32 v137, 0xffff0000, v191
	v_pk_mul_f32 v[130:131], v[130:131], s[28:29] op_sel_hi:[1,0]
	v_pk_mul_f32 v[132:133], v[132:133], s[28:29] op_sel_hi:[1,0]
	v_pk_fma_f32 v[108:109], v[108:109], 0.5, v[130:131] op_sel_hi:[1,0,1]
	v_pk_fma_f32 v[110:111], v[110:111], 0.5, v[132:133] op_sel_hi:[1,0,1]
	v_pk_mul_f32 v[130:131], v[134:135], s[28:29] op_sel_hi:[1,0]
	v_pk_mul_f32 v[132:133], v[136:137], s[28:29] op_sel_hi:[1,0]
	v_pk_fma_f32 v[104:105], v[104:105], 0.5, v[130:131] op_sel_hi:[1,0,1]
	v_pk_fma_f32 v[106:107], v[106:107], 0.5, v[132:133] op_sel_hi:[1,0,1]
	v_lshlrev_b32_e32 v130, 16, v192
	v_and_b32_e32 v131, 0xffff0000, v192
	v_lshlrev_b32_e32 v132, 16, v193
	v_and_b32_e32 v133, 0xffff0000, v193
	v_lshlrev_b32_e32 v134, 16, v194
	v_and_b32_e32 v135, 0xffff0000, v194
	v_lshlrev_b32_e32 v136, 16, v195
	v_and_b32_e32 v137, 0xffff0000, v195
	v_pk_mul_f32 v[130:131], v[130:131], s[28:29] op_sel_hi:[1,0]
	v_pk_mul_f32 v[132:133], v[132:133], s[28:29] op_sel_hi:[1,0]
	v_lshlrev_b32_e32 v146, 16, v138
	v_and_b32_e32 v147, 0xffff0000, v138
	v_lshlrev_b32_e32 v138, 16, v139
	v_and_b32_e32 v139, 0xffff0000, v139
	v_lshlrev_b32_e32 v158, 16, v140
	v_and_b32_e32 v159, 0xffff0000, v140
	v_lshlrev_b32_e32 v140, 16, v141
	v_and_b32_e32 v141, 0xffff0000, v141
	v_pk_fma_f32 v[30:31], v[30:31], 0.5, v[132:133] op_sel_hi:[1,0,1]
	v_pk_fma_f32 v[28:29], v[28:29], 0.5, v[130:131] op_sel_hi:[1,0,1]
	v_pk_mul_f32 v[130:131], v[134:135], s[28:29] op_sel_hi:[1,0]
	v_pk_mul_f32 v[132:133], v[136:137], s[28:29] op_sel_hi:[1,0]
	v_pk_fma_f32 v[14:15], v[138:139], s[28:29], v[174:175] op_sel_hi:[1,0,1]
	v_pk_fma_f32 v[12:13], v[146:147], s[28:29], v[196:197] op_sel_hi:[1,0,1]
	v_pk_fma_f32 v[10:11], v[140:141], s[28:29], v[198:199] op_sel_hi:[1,0,1]
	v_pk_fma_f32 v[8:9], v[158:159], s[28:29], v[200:201] op_sel_hi:[1,0,1]
	v_pk_fma_f32 v[26:27], v[26:27], 0.5, v[132:133] op_sel_hi:[1,0,1]
	v_pk_fma_f32 v[24:25], v[24:25], 0.5, v[130:131] op_sel_hi:[1,0,1]
	v_add_co_u32_e32 v142, vcc, s71, v128
	s_nop 1
	v_addc_co_u32_e32 v143, vcc, 0, v129, vcc
	global_load_dwordx4 v[130:133], v[142:143], off offset:-4096 nt
	v_add_co_u32_e32 v144, vcc, s78, v128
	v_pk_add_f32 v[174:175], v[94:95], v[90:91]
	s_nop 0
	v_addc_co_u32_e32 v145, vcc, 0, v129, vcc
	global_load_dwordx4 v[134:137], v[144:145], off offset:-4096 nt
	v_add_co_u32_e32 v138, vcc, s3, v128
	s_nop 1
	v_addc_co_u32_e32 v139, vcc, 0, v129, vcc
	global_load_dwordx4 v[138:141], v[138:139], off offset:2048 nt
	v_add_co_u32_e32 v128, vcc, s70, v128
	s_nop 1
	v_addc_co_u32_e32 v129, vcc, 0, v129, vcc
	global_load_dwordx4 v[150:153], v[128:129], off offset:2048 nt
	global_load_dwordx4 v[154:157], v[142:143], off nt
	global_load_dwordx4 v[188:191], v[142:143], off offset:2048 nt
	global_load_dwordx4 v[192:195], v[144:145], off nt
	s_nop 0
	global_load_dwordx4 v[144:147], v[144:145], off offset:2048 nt
	v_cmp_eq_u32_e32 vcc, 0, v187
	s_waitcnt vmcnt(7)
	v_lshlrev_b32_e32 v128, 16, v130
	v_and_b32_e32 v129, 0xffff0000, v130
	v_lshlrev_b32_e32 v142, 16, v132
	v_and_b32_e32 v143, 0xffff0000, v132
	v_pk_mul_f32 v[128:129], v[128:129], s[28:29] op_sel_hi:[1,0]
	v_lshlrev_b32_e32 v130, 16, v131
	v_and_b32_e32 v131, 0xffff0000, v131
	v_pk_fma_f32 v[116:117], v[116:117], 0.5, v[128:129] op_sel_hi:[1,0,1]
	v_pk_mul_f32 v[128:129], v[142:143], s[28:29] op_sel_hi:[1,0]
	v_lshlrev_b32_e32 v132, 16, v133
	v_and_b32_e32 v133, 0xffff0000, v133
	v_pk_mul_f32 v[130:131], v[130:131], s[28:29] op_sel_hi:[1,0]
	v_pk_fma_f32 v[112:113], v[112:113], 0.5, v[128:129] op_sel_hi:[1,0,1]
	s_waitcnt vmcnt(6)
	v_lshlrev_b32_e32 v128, 16, v134
	v_and_b32_e32 v129, 0xffff0000, v134
	v_pk_fma_f32 v[118:119], v[118:119], 0.5, v[130:131] op_sel_hi:[1,0,1]
	v_pk_mul_f32 v[130:131], v[132:133], s[28:29] op_sel_hi:[1,0]
	v_lshlrev_b32_e32 v132, 16, v136
	v_and_b32_e32 v133, 0xffff0000, v136
	v_pk_mul_f32 v[128:129], v[128:129], s[28:29] op_sel_hi:[1,0]
	v_pk_fma_f32 v[114:115], v[114:115], 0.5, v[130:131] op_sel_hi:[1,0,1]
	v_lshlrev_b32_e32 v130, 16, v135
	v_and_b32_e32 v131, 0xffff0000, v135
	v_pk_fma_f32 v[36:37], v[36:37], 0.5, v[128:129] op_sel_hi:[1,0,1]
	v_pk_mul_f32 v[128:129], v[132:133], s[28:29] op_sel_hi:[1,0]
	v_lshlrev_b32_e32 v134, 16, v137
	v_and_b32_e32 v135, 0xffff0000, v137
	v_pk_mul_f32 v[130:131], v[130:131], s[28:29] op_sel_hi:[1,0]
	v_pk_fma_f32 v[32:33], v[32:33], 0.5, v[128:129] op_sel_hi:[1,0,1]
	s_waitcnt vmcnt(5)
	v_lshlrev_b32_e32 v128, 16, v138
	v_and_b32_e32 v129, 0xffff0000, v138
	v_pk_fma_f32 v[38:39], v[38:39], 0.5, v[130:131] op_sel_hi:[1,0,1]
	v_pk_mul_f32 v[130:131], v[134:135], s[28:29] op_sel_hi:[1,0]
	v_lshlrev_b32_e32 v132, 16, v140
	v_and_b32_e32 v133, 0xffff0000, v140
	v_pk_mul_f32 v[128:129], v[128:129], s[28:29] op_sel_hi:[1,0]
	v_pk_fma_f32 v[34:35], v[34:35], 0.5, v[130:131] op_sel_hi:[1,0,1]
	v_lshlrev_b32_e32 v130, 16, v139
	v_and_b32_e32 v131, 0xffff0000, v139
	v_pk_fma_f32 v[124:125], v[124:125], 0.5, v[128:129] op_sel_hi:[1,0,1]
	v_pk_mul_f32 v[128:129], v[132:133], s[28:29] op_sel_hi:[1,0]
	v_lshlrev_b32_e32 v134, 16, v141
	v_and_b32_e32 v135, 0xffff0000, v141
	v_pk_mul_f32 v[130:131], v[130:131], s[28:29] op_sel_hi:[1,0]
	v_pk_fma_f32 v[120:121], v[120:121], 0.5, v[128:129] op_sel_hi:[1,0,1]
	s_waitcnt vmcnt(4)
	v_lshlrev_b32_e32 v128, 16, v150
	v_and_b32_e32 v129, 0xffff0000, v150
	v_pk_fma_f32 v[126:127], v[126:127], 0.5, v[130:131] op_sel_hi:[1,0,1]
	v_pk_mul_f32 v[130:131], v[134:135], s[28:29] op_sel_hi:[1,0]
	v_lshlrev_b32_e32 v132, 16, v152
	v_and_b32_e32 v133, 0xffff0000, v152
	v_pk_mul_f32 v[128:129], v[128:129], s[28:29] op_sel_hi:[1,0]
	v_pk_fma_f32 v[122:123], v[122:123], 0.5, v[130:131] op_sel_hi:[1,0,1]
	v_lshlrev_b32_e32 v130, 16, v151
	v_and_b32_e32 v131, 0xffff0000, v151
	v_pk_fma_f32 v[44:45], v[44:45], 0.5, v[128:129] op_sel_hi:[1,0,1]
	v_pk_mul_f32 v[128:129], v[132:133], s[28:29] op_sel_hi:[1,0]
	v_lshlrev_b32_e32 v134, 16, v153
	v_and_b32_e32 v135, 0xffff0000, v153
	v_pk_mul_f32 v[130:131], v[130:131], s[28:29] op_sel_hi:[1,0]
	v_pk_fma_f32 v[40:41], v[40:41], 0.5, v[128:129] op_sel_hi:[1,0,1]
	s_waitcnt vmcnt(3)
	v_lshlrev_b32_e32 v128, 16, v154
	v_and_b32_e32 v129, 0xffff0000, v154
	v_pk_fma_f32 v[46:47], v[46:47], 0.5, v[130:131] op_sel_hi:[1,0,1]
	v_pk_mul_f32 v[130:131], v[134:135], s[28:29] op_sel_hi:[1,0]
	v_lshlrev_b32_e32 v136, 16, v156
	v_and_b32_e32 v137, 0xffff0000, v156
	v_pk_mul_f32 v[128:129], v[128:129], s[28:29] op_sel_hi:[1,0]
	v_pk_fma_f32 v[42:43], v[42:43], 0.5, v[130:131] op_sel_hi:[1,0,1]
	v_lshlrev_b32_e32 v130, 16, v155
	v_and_b32_e32 v131, 0xffff0000, v155
	v_pk_fma_f32 v[132:133], v[76:77], 0.5, v[128:129] op_sel_hi:[1,0,1]
	v_pk_mul_f32 v[76:77], v[136:137], s[28:29] op_sel_hi:[1,0]
	v_lshlrev_b32_e32 v138, 16, v157
	v_and_b32_e32 v139, 0xffff0000, v157
	v_pk_mul_f32 v[130:131], v[130:131], s[28:29] op_sel_hi:[1,0]
	v_pk_fma_f32 v[128:129], v[72:73], 0.5, v[76:77] op_sel_hi:[1,0,1]
	s_waitcnt vmcnt(1)
	v_lshlrev_b32_e32 v72, 16, v192
	v_and_b32_e32 v73, 0xffff0000, v192
	v_pk_fma_f32 v[134:135], v[78:79], 0.5, v[130:131] op_sel_hi:[1,0,1]
	v_pk_mul_f32 v[78:79], v[138:139], s[28:29] op_sel_hi:[1,0]
	v_lshlrev_b32_e32 v76, 16, v194
	v_and_b32_e32 v77, 0xffff0000, v194
	v_pk_mul_f32 v[72:73], v[72:73], s[28:29] op_sel_hi:[1,0]
	v_pk_fma_f32 v[130:131], v[74:75], 0.5, v[78:79] op_sel_hi:[1,0,1]
	v_lshlrev_b32_e32 v74, 16, v193
	v_and_b32_e32 v75, 0xffff0000, v193
	v_pk_fma_f32 v[52:53], v[52:53], 0.5, v[72:73] op_sel_hi:[1,0,1]
	v_pk_mul_f32 v[72:73], v[76:77], s[28:29] op_sel_hi:[1,0]
	v_lshlrev_b32_e32 v78, 16, v195
	v_and_b32_e32 v79, 0xffff0000, v195
	v_pk_mul_f32 v[74:75], v[74:75], s[28:29] op_sel_hi:[1,0]
	v_pk_fma_f32 v[48:49], v[48:49], 0.5, v[72:73] op_sel_hi:[1,0,1]
	v_lshlrev_b32_e32 v72, 16, v188
	v_and_b32_e32 v73, 0xffff0000, v188
	v_pk_fma_f32 v[54:55], v[54:55], 0.5, v[74:75] op_sel_hi:[1,0,1]
	v_pk_mul_f32 v[74:75], v[78:79], s[28:29] op_sel_hi:[1,0]
	v_lshlrev_b32_e32 v76, 16, v190
	v_and_b32_e32 v77, 0xffff0000, v190
	v_pk_mul_f32 v[72:73], v[72:73], s[28:29] op_sel_hi:[1,0]
	v_pk_fma_f32 v[50:51], v[50:51], 0.5, v[74:75] op_sel_hi:[1,0,1]
	v_lshlrev_b32_e32 v74, 16, v189
	v_and_b32_e32 v75, 0xffff0000, v189
	v_pk_fma_f32 v[140:141], v[68:69], 0.5, v[72:73] op_sel_hi:[1,0,1]
	v_pk_mul_f32 v[68:69], v[76:77], s[28:29] op_sel_hi:[1,0]
	v_lshlrev_b32_e32 v78, 16, v191
	v_and_b32_e32 v79, 0xffff0000, v191
	v_pk_mul_f32 v[74:75], v[74:75], s[28:29] op_sel_hi:[1,0]
	v_pk_fma_f32 v[136:137], v[64:65], 0.5, v[68:69] op_sel_hi:[1,0,1]
	s_waitcnt vmcnt(0)
	v_lshlrev_b32_e32 v64, 16, v144
	v_and_b32_e32 v65, 0xffff0000, v144
	v_pk_fma_f32 v[142:143], v[70:71], 0.5, v[74:75] op_sel_hi:[1,0,1]
	v_pk_mul_f32 v[70:71], v[78:79], s[28:29] op_sel_hi:[1,0]
	v_lshlrev_b32_e32 v68, 16, v146
	v_and_b32_e32 v69, 0xffff0000, v146
	v_pk_mul_f32 v[64:65], v[64:65], s[28:29] op_sel_hi:[1,0]
	v_pk_fma_f32 v[138:139], v[66:67], 0.5, v[70:71] op_sel_hi:[1,0,1]
	v_lshlrev_b32_e32 v66, 16, v145
	v_and_b32_e32 v67, 0xffff0000, v145
	v_pk_fma_f32 v[60:61], v[60:61], 0.5, v[64:65] op_sel_hi:[1,0,1]
	v_pk_mul_f32 v[64:65], v[68:69], s[28:29] op_sel_hi:[1,0]
	v_lshlrev_b32_e32 v70, 16, v147
	v_and_b32_e32 v71, 0xffff0000, v147
	v_pk_mul_f32 v[66:67], v[66:67], s[28:29] op_sel_hi:[1,0]
	v_pk_fma_f32 v[56:57], v[56:57], 0.5, v[64:65] op_sel_hi:[1,0,1]
	v_add_u32_e32 v64, s6, v148
	v_pk_fma_f32 v[62:63], v[62:63], 0.5, v[66:67] op_sel_hi:[1,0,1]
	v_pk_mul_f32 v[66:67], v[70:71], s[28:29] op_sel_hi:[1,0]
	v_ashrrev_i32_e32 v65, 31, v64
	v_pk_fma_f32 v[58:59], v[58:59], 0.5, v[66:67] op_sel_hi:[1,0,1]
	v_lshlrev_b64 v[64:65], 2, v[64:65]
	v_lshl_add_u64 v[68:69], s[20:21], 0, v[64:65]
	v_lshl_add_u64 v[76:77], s[22:23], 0, v[64:65]
	global_load_dwordx4 v[144:147], v[68:69], off offset:16
	global_load_dwordx4 v[152:155], v[68:69], off
	global_load_dwordx4 v[148:151], v[76:77], off offset:16
	global_load_dwordx4 v[156:159], v[76:77], off
	global_load_dwordx4 v[64:67], v[68:69], off offset:528
	global_load_dwordx4 v[72:75], v[68:69], off offset:512
	s_nop 0
	global_load_dwordx4 v[68:71], v[76:77], off offset:528
	s_nop 0
	global_load_dwordx4 v[76:79], v[76:77], off offset:512
	v_pk_add_f32 v[188:189], v[92:93], v[88:89]
	v_pk_add_f32 v[190:191], v[14:15], v[10:11]
	v_pk_add_f32 v[192:193], v[12:13], v[8:9]
	v_pk_add_f32 v[174:175], v[174:175], v[190:191]
	v_pk_add_f32 v[188:189], v[188:189], v[192:193]
	v_add_f32_e32 v174, v174, v175
	v_add_f32_e32 v188, v188, v189
	v_add_f32_e32 v174, v188, v174
	v_mov_b32_e32 v175, v174
	s_nop 1
	v_permlane16_swap_b32_e32 v174, v175
	v_add_f32_e32 v174, v174, v175
	v_mov_b32_e32 v175, v174
	s_nop 1
	v_permlane32_swap_b32_e32 v174, v175
	v_add_f32_e32 v174, v174, v175
	v_fmamk_f32 v193, v174, 0xbc800000, v89
	v_fmamk_f32 v192, v174, 0xbc800000, v88
	v_fmamk_f32 v195, v174, 0xbc800000, v91
	v_fmamk_f32 v194, v174, 0xbc800000, v90
	v_fmamk_f32 v189, v174, 0xbc800000, v95
	v_fmamk_f32 v188, v174, 0xbc800000, v94
	v_fmamk_f32 v191, v174, 0xbc800000, v93
	v_fmamk_f32 v190, v174, 0xbc800000, v92
	v_fmamk_f32 v201, v174, 0xbc800000, v9
	v_fmamk_f32 v200, v174, 0xbc800000, v8
	v_fmamk_f32 v203, v174, 0xbc800000, v11
	v_fmamk_f32 v202, v174, 0xbc800000, v10
	v_pk_mul_f32 v[194:195], v[194:195], v[194:195]
	v_pk_mul_f32 v[192:193], v[192:193], v[192:193]
	v_fmamk_f32 v197, v174, 0xbc800000, v15
	v_fmamk_f32 v196, v174, 0xbc800000, v14
	v_fmamk_f32 v199, v174, 0xbc800000, v13
	v_fmamk_f32 v198, v174, 0xbc800000, v12
	v_pk_fma_f32 v[190:191], v[190:191], v[190:191], v[192:193]
	v_pk_fma_f32 v[188:189], v[188:189], v[188:189], v[194:195]
	v_pk_mul_f32 v[192:193], v[202:203], v[202:203]
	v_pk_mul_f32 v[194:195], v[200:201], v[200:201]
	v_pk_fma_f32 v[192:193], v[196:197], v[196:197], v[192:193]
	v_pk_fma_f32 v[194:195], v[198:199], v[198:199], v[194:195]
	v_pk_add_f32 v[188:189], v[188:189], v[192:193]
	v_pk_add_f32 v[190:191], v[190:191], v[194:195]
	v_add_f32_e32 v188, v188, v189
	v_add_f32_e32 v175, v190, v191
	v_add_f32_e32 v175, v175, v188
	v_mov_b32_e32 v188, v175
	s_nop 1
	v_permlane16_swap_b32_e32 v175, v188
	s_lshl_b32 s6, s8, 3
	v_add_f32_e32 v175, v175, v188
	s_add_i32 s11, s6, 0
	v_mov_b32_e32 v188, v175
	s_add_i32 s11, s11, 0x21000
	s_nop 0
	v_permlane32_swap_b32_e32 v175, v188
	s_and_saveexec_b64 s[6:7], vcc
	s_cbranch_execz .LBB0_1711
	s_lshl_b32 s15, s9, 11
	s_add_i32 s15, s11, s15
	v_mul_f32_e32 v174, 0x3c800000, v174
	v_lshl_add_u32 v189, v186, 5, s15
	v_add_f32_e32 v175, v175, v188
	ds_write_b64 v189, v[174:175]

.LBB0_1903:
	v_mov_b32_e32 v187, v178
	s_mov_b32 s8, s68
	v_mov_b32_e32 v186, v177
	s_mov_b32 s9, s55
	s_lshl_b32 s7, s14, 2
	s_ashr_i32 s10, s8, 1
	s_lshl_b32 s31, s9, 6
	s_add_i32 s38, s10, s7
	s_lshl_b32 s10, s40, 8
	s_lshl_b32 s6, s8, 5
	s_ashr_i32 s39, s38, 31
	s_add_i32 s51, s31, s10
	v_add_u32_e32 v128, s51, v186
	s_and_b32 s7, s6, 32
	s_lshl_b64 s[38:39], s[38:39], 22
	v_ashrrev_i32_e32 v129, 31, v128
	s_add_u32 s38, s58, s38
	v_lshlrev_b64 v[128:129], 7, v[128:129]
	s_addc_u32 s39, s59, s39
	v_lshlrev_b32_e32 v148, 3, v187
	v_lshl_add_u64 v[128:129], s[38:39], 0, v[128:129]
	s_lshl_b32 s12, s7, 1
	v_ashrrev_i32_e32 v149, 31, v148
	v_lshl_add_u64 v[128:129], v[128:129], 0, s[12:13]
	v_lshl_add_u64 v[128:129], v[148:149], 1, v[128:129]
	v_add_co_u32_e32 v146, vcc, s71, v128
	global_load_dwordx4 v[130:133], v[128:129], off nt
	global_load_dwordx4 v[134:137], v[128:129], off offset:2048 nt
	v_addc_co_u32_e32 v147, vcc, 0, v129, vcc
	v_add_co_u32_e32 v142, vcc, s69, v128
	global_load_dwordx4 v[138:141], v[146:147], off offset:-4096 nt
	s_nop 0
	v_addc_co_u32_e32 v143, vcc, 0, v129, vcc
	global_load_dwordx4 v[142:145], v[142:143], off offset:2048 nt
	v_add_co_u32_e32 v158, vcc, s70, v128
	global_load_dwordx4 v[154:157], v[146:147], off nt
	s_nop 0
	v_addc_co_u32_e32 v159, vcc, 0, v129, vcc
	global_load_dwordx4 v[150:153], v[158:159], off nt
	global_load_dwordx4 v[188:191], v[158:159], off offset:2048 nt
	global_load_dwordx4 v[192:195], v[146:147], off offset:2048 nt
	v_pk_mul_f32 v[90:91], v[90:91], 0.5 op_sel_hi:[1,0]
	v_pk_mul_f32 v[88:89], v[88:89], 0.5 op_sel_hi:[1,0]
	v_pk_mul_f32 v[174:175], v[86:87], 0.5 op_sel_hi:[1,0]
	v_pk_mul_f32 v[196:197], v[84:85], 0.5 op_sel_hi:[1,0]
	v_pk_mul_f32 v[198:199], v[82:83], 0.5 op_sel_hi:[1,0]
	v_pk_mul_f32 v[200:201], v[80:81], 0.5 op_sel_hi:[1,0]
	v_pk_mul_f32 v[14:15], v[14:15], 0.5 op_sel_hi:[1,0]
	v_pk_mul_f32 v[12:13], v[12:13], 0.5 op_sel_hi:[1,0]
	v_pk_mul_f32 v[94:95], v[94:95], 0.5 op_sel_hi:[1,0]
	v_pk_mul_f32 v[92:93], v[92:93], 0.5 op_sel_hi:[1,0]
	v_pk_mul_f32 v[10:11], v[10:11], 0.5 op_sel_hi:[1,0]
	v_pk_mul_f32 v[8:9], v[8:9], 0.5 op_sel_hi:[1,0]
	s_lshl_b32 s7, s14, 8
	s_add_i32 s6, s6, s7
	s_waitcnt vmcnt(0)
	v_lshlrev_b32_e32 v80, 16, v130
	v_and_b32_e32 v81, 0xffff0000, v130
	v_lshlrev_b32_e32 v82, 16, v131
	v_and_b32_e32 v83, 0xffff0000, v131
	v_lshlrev_b32_e32 v84, 16, v132
	v_and_b32_e32 v85, 0xffff0000, v132
	v_lshlrev_b32_e32 v86, 16, v133
	v_and_b32_e32 v87, 0xffff0000, v133
	v_lshlrev_b32_e32 v130, 16, v134
	v_and_b32_e32 v131, 0xffff0000, v134
	v_lshlrev_b32_e32 v132, 16, v135
	v_and_b32_e32 v133, 0xffff0000, v135
	v_lshlrev_b32_e32 v134, 16, v136
	v_and_b32_e32 v135, 0xffff0000, v136
	v_lshlrev_b32_e32 v136, 16, v137
	v_and_b32_e32 v137, 0xffff0000, v137
	v_pk_fma_f32 v[90:91], v[86:87], s[28:29], v[90:91] op_sel_hi:[1,0,1]
	v_pk_fma_f32 v[88:89], v[84:85], s[28:29], v[88:89] op_sel_hi:[1,0,1]
	v_pk_fma_f32 v[86:87], v[132:133], s[28:29], v[14:15] op_sel_hi:[1,0,1]
	v_pk_fma_f32 v[84:85], v[130:131], s[28:29], v[12:13] op_sel_hi:[1,0,1]
	v_lshlrev_b32_e32 v130, 16, v142
	v_and_b32_e32 v131, 0xffff0000, v142
	v_lshlrev_b32_e32 v132, 16, v143
	v_and_b32_e32 v133, 0xffff0000, v143
	v_pk_fma_f32 v[94:95], v[82:83], s[28:29], v[94:95] op_sel_hi:[1,0,1]
	v_pk_fma_f32 v[92:93], v[80:81], s[28:29], v[92:93] op_sel_hi:[1,0,1]
	v_pk_fma_f32 v[82:83], v[136:137], s[28:29], v[10:11] op_sel_hi:[1,0,1]
	v_pk_fma_f32 v[80:81], v[134:135], s[28:29], v[8:9] op_sel_hi:[1,0,1]
	v_lshlrev_b32_e32 v134, 16, v144
	v_and_b32_e32 v135, 0xffff0000, v144
	v_lshlrev_b32_e32 v136, 16, v145
	v_and_b32_e32 v137, 0xffff0000, v145
	v_pk_mul_f32 v[130:131], v[130:131], s[28:29] op_sel_hi:[1,0]
	v_pk_mul_f32 v[132:133], v[132:133], s[28:29] op_sel_hi:[1,0]
	v_pk_fma_f32 v[4:5], v[4:5], 0.5, v[130:131] op_sel_hi:[1,0,1]
	v_pk_fma_f32 v[6:7], v[6:7], 0.5, v[132:133] op_sel_hi:[1,0,1]
	v_pk_mul_f32 v[130:131], v[134:135], s[28:29] op_sel_hi:[1,0]
	v_pk_mul_f32 v[132:133], v[136:137], s[28:29] op_sel_hi:[1,0]
	v_pk_fma_f32 v[0:1], v[0:1], 0.5, v[130:131] op_sel_hi:[1,0,1]
	v_pk_fma_f32 v[2:3], v[2:3], 0.5, v[132:133] op_sel_hi:[1,0,1]
	v_lshlrev_b32_e32 v130, 16, v150
	v_and_b32_e32 v131, 0xffff0000, v150
	v_lshlrev_b32_e32 v132, 16, v151
	v_and_b32_e32 v133, 0xffff0000, v151
	v_lshlrev_b32_e32 v134, 16, v152
	v_and_b32_e32 v135, 0xffff0000, v152
	v_lshlrev_b32_e32 v136, 16, v153
	v_and_b32_e32 v137, 0xffff0000, v153
	v_pk_mul_f32 v[130:131], v[130:131], s[28:29] op_sel_hi:[1,0]
	v_pk_mul_f32 v[132:133], v[132:133], s[28:29] op_sel_hi:[1,0]
	v_pk_fma_f32 v[100:101], v[100:101], 0.5, v[130:131] op_sel_hi:[1,0,1]
	v_pk_fma_f32 v[102:103], v[102:103], 0.5, v[132:133] op_sel_hi:[1,0,1]
	v_pk_mul_f32 v[130:131], v[134:135], s[28:29] op_sel_hi:[1,0]
	v_pk_mul_f32 v[132:133], v[136:137], s[28:29] op_sel_hi:[1,0]
	v_pk_fma_f32 v[96:97], v[96:97], 0.5, v[130:131] op_sel_hi:[1,0,1]
	v_pk_fma_f32 v[98:99], v[98:99], 0.5, v[132:133] op_sel_hi:[1,0,1]
	v_lshlrev_b32_e32 v130, 16, v154
	v_and_b32_e32 v131, 0xffff0000, v154
	v_lshlrev_b32_e32 v132, 16, v155
	v_and_b32_e32 v133, 0xffff0000, v155
	v_lshlrev_b32_e32 v134, 16, v156
	v_and_b32_e32 v135, 0xffff0000, v156
	v_lshlrev_b32_e32 v136, 16, v157
	v_and_b32_e32 v137, 0xffff0000, v157
	v_pk_mul_f32 v[130:131], v[130:131], s[28:29] op_sel_hi:[1,0]
	v_pk_mul_f32 v[132:133], v[132:133], s[28:29] op_sel_hi:[1,0]
	v_pk_fma_f32 v[20:21], v[20:21], 0.5, v[130:131] op_sel_hi:[1,0,1]
	v_pk_fma_f32 v[22:23], v[22:23], 0.5, v[132:133] op_sel_hi:[1,0,1]
	v_pk_mul_f32 v[130:131], v[134:135], s[28:29] op_sel_hi:[1,0]
	v_pk_mul_f32 v[132:133], v[136:137], s[28:29] op_sel_hi:[1,0]
	v_pk_fma_f32 v[16:17], v[16:17], 0.5, v[130:131] op_sel_hi:[1,0,1]
	v_pk_fma_f32 v[18:19], v[18:19], 0.5, v[132:133] op_sel_hi:[1,0,1]
	v_lshlrev_b32_e32 v130, 16, v188
	v_and_b32_e32 v131, 0xffff0000, v188
	v_lshlrev_b32_e32 v132, 16, v189
	v_and_b32_e32 v133, 0xffff0000, v189
	v_lshlrev_b32_e32 v134, 16, v190
	v_and_b32_e32 v135, 0xffff0000, v190
	v_lshlrev_b32_e32 v136, 16, v191
	v_and_b32_e32 v137, 0xffff0000, v191
	v_pk_mul_f32 v[130:131], v[130:131], s[28:29] op_sel_hi:[1,0]
	v_pk_mul_f32 v[132:133], v[132:133], s[28:29] op_sel_hi:[1,0]
	v_pk_fma_f32 v[108:109], v[108:109], 0.5, v[130:131] op_sel_hi:[1,0,1]
	v_pk_fma_f32 v[110:111], v[110:111], 0.5, v[132:133] op_sel_hi:[1,0,1]
	v_pk_mul_f32 v[130:131], v[134:135], s[28:29] op_sel_hi:[1,0]
	v_pk_mul_f32 v[132:133], v[136:137], s[28:29] op_sel_hi:[1,0]
	v_pk_fma_f32 v[104:105], v[104:105], 0.5, v[130:131] op_sel_hi:[1,0,1]
	v_pk_fma_f32 v[106:107], v[106:107], 0.5, v[132:133] op_sel_hi:[1,0,1]
	v_lshlrev_b32_e32 v130, 16, v192
	v_and_b32_e32 v131, 0xffff0000, v192
	v_lshlrev_b32_e32 v132, 16, v193
	v_and_b32_e32 v133, 0xffff0000, v193
	v_lshlrev_b32_e32 v134, 16, v194
	v_and_b32_e32 v135, 0xffff0000, v194
	v_lshlrev_b32_e32 v136, 16, v195
	v_and_b32_e32 v137, 0xffff0000, v195
	v_pk_mul_f32 v[130:131], v[130:131], s[28:29] op_sel_hi:[1,0]
	v_pk_mul_f32 v[132:133], v[132:133], s[28:29] op_sel_hi:[1,0]
	v_lshlrev_b32_e32 v146, 16, v138
	v_and_b32_e32 v147, 0xffff0000, v138
	v_lshlrev_b32_e32 v138, 16, v139
	v_and_b32_e32 v139, 0xffff0000, v139
	v_lshlrev_b32_e32 v158, 16, v140
	v_and_b32_e32 v159, 0xffff0000, v140
	v_lshlrev_b32_e32 v140, 16, v141
	v_and_b32_e32 v141, 0xffff0000, v141
	v_pk_fma_f32 v[30:31], v[30:31], 0.5, v[132:133] op_sel_hi:[1,0,1]
	v_pk_fma_f32 v[28:29], v[28:29], 0.5, v[130:131] op_sel_hi:[1,0,1]
	v_pk_mul_f32 v[130:131], v[134:135], s[28:29] op_sel_hi:[1,0]
	v_pk_mul_f32 v[132:133], v[136:137], s[28:29] op_sel_hi:[1,0]
	v_pk_fma_f32 v[14:15], v[138:139], s[28:29], v[174:175] op_sel_hi:[1,0,1]
	v_pk_fma_f32 v[12:13], v[146:147], s[28:29], v[196:197] op_sel_hi:[1,0,1]
	v_pk_fma_f32 v[10:11], v[140:141], s[28:29], v[198:199] op_sel_hi:[1,0,1]
	v_pk_fma_f32 v[8:9], v[158:159], s[28:29], v[200:201] op_sel_hi:[1,0,1]
	v_pk_fma_f32 v[26:27], v[26:27], 0.5, v[132:133] op_sel_hi:[1,0,1]
	v_pk_fma_f32 v[24:25], v[24:25], 0.5, v[130:131] op_sel_hi:[1,0,1]
	v_add_co_u32_e32 v142, vcc, s33, v128
	s_nop 1
	v_addc_co_u32_e32 v143, vcc, 0, v129, vcc
	global_load_dwordx4 v[130:133], v[142:143], off offset:-4096 nt
	v_add_co_u32_e32 v144, vcc, s88, v128
	v_pk_add_f32 v[174:175], v[94:95], v[90:91]
	s_nop 0
	v_addc_co_u32_e32 v145, vcc, 0, v129, vcc
	global_load_dwordx4 v[134:137], v[144:145], off offset:-4096 nt
	v_add_co_u32_e32 v138, vcc, s3, v128
	s_nop 1
	v_addc_co_u32_e32 v139, vcc, 0, v129, vcc
	global_load_dwordx4 v[138:141], v[138:139], off offset:2048 nt
	v_add_co_u32_e32 v128, vcc, s56, v128
	s_nop 1
	v_addc_co_u32_e32 v129, vcc, 0, v129, vcc
	global_load_dwordx4 v[150:153], v[128:129], off offset:2048 nt
	global_load_dwordx4 v[154:157], v[142:143], off nt
	global_load_dwordx4 v[188:191], v[142:143], off offset:2048 nt
	global_load_dwordx4 v[192:195], v[144:145], off nt
	s_nop 0
	global_load_dwordx4 v[144:147], v[144:145], off offset:2048 nt
	v_cmp_eq_u32_e32 vcc, 0, v187
	s_waitcnt vmcnt(7)
	v_lshlrev_b32_e32 v128, 16, v130
	v_and_b32_e32 v129, 0xffff0000, v130
	v_lshlrev_b32_e32 v142, 16, v132
	v_and_b32_e32 v143, 0xffff0000, v132
	v_pk_mul_f32 v[128:129], v[128:129], s[28:29] op_sel_hi:[1,0]
	v_lshlrev_b32_e32 v130, 16, v131
	v_and_b32_e32 v131, 0xffff0000, v131
	v_pk_fma_f32 v[116:117], v[116:117], 0.5, v[128:129] op_sel_hi:[1,0,1]
	v_pk_mul_f32 v[128:129], v[142:143], s[28:29] op_sel_hi:[1,0]
	v_lshlrev_b32_e32 v132, 16, v133
	v_and_b32_e32 v133, 0xffff0000, v133
	v_pk_mul_f32 v[130:131], v[130:131], s[28:29] op_sel_hi:[1,0]
	v_pk_fma_f32 v[112:113], v[112:113], 0.5, v[128:129] op_sel_hi:[1,0,1]
	s_waitcnt vmcnt(6)
	v_lshlrev_b32_e32 v128, 16, v134
	v_and_b32_e32 v129, 0xffff0000, v134
	v_pk_fma_f32 v[118:119], v[118:119], 0.5, v[130:131] op_sel_hi:[1,0,1]
	v_pk_mul_f32 v[130:131], v[132:133], s[28:29] op_sel_hi:[1,0]
	v_lshlrev_b32_e32 v132, 16, v136
	v_and_b32_e32 v133, 0xffff0000, v136
	v_pk_mul_f32 v[128:129], v[128:129], s[28:29] op_sel_hi:[1,0]
	v_pk_fma_f32 v[114:115], v[114:115], 0.5, v[130:131] op_sel_hi:[1,0,1]
	v_lshlrev_b32_e32 v130, 16, v135
	v_and_b32_e32 v131, 0xffff0000, v135
	v_pk_fma_f32 v[36:37], v[36:37], 0.5, v[128:129] op_sel_hi:[1,0,1]
	v_pk_mul_f32 v[128:129], v[132:133], s[28:29] op_sel_hi:[1,0]
	v_lshlrev_b32_e32 v134, 16, v137
	v_and_b32_e32 v135, 0xffff0000, v137
	v_pk_mul_f32 v[130:131], v[130:131], s[28:29] op_sel_hi:[1,0]
	v_pk_fma_f32 v[32:33], v[32:33], 0.5, v[128:129] op_sel_hi:[1,0,1]
	s_waitcnt vmcnt(5)
	v_lshlrev_b32_e32 v128, 16, v138
	v_and_b32_e32 v129, 0xffff0000, v138
	v_pk_fma_f32 v[38:39], v[38:39], 0.5, v[130:131] op_sel_hi:[1,0,1]
	v_pk_mul_f32 v[130:131], v[134:135], s[28:29] op_sel_hi:[1,0]
	v_lshlrev_b32_e32 v132, 16, v140
	v_and_b32_e32 v133, 0xffff0000, v140
	v_pk_mul_f32 v[128:129], v[128:129], s[28:29] op_sel_hi:[1,0]
	v_pk_fma_f32 v[34:35], v[34:35], 0.5, v[130:131] op_sel_hi:[1,0,1]
	v_lshlrev_b32_e32 v130, 16, v139
	v_and_b32_e32 v131, 0xffff0000, v139
	v_pk_fma_f32 v[124:125], v[124:125], 0.5, v[128:129] op_sel_hi:[1,0,1]
	v_pk_mul_f32 v[128:129], v[132:133], s[28:29] op_sel_hi:[1,0]
	v_lshlrev_b32_e32 v134, 16, v141
	v_and_b32_e32 v135, 0xffff0000, v141
	v_pk_mul_f32 v[130:131], v[130:131], s[28:29] op_sel_hi:[1,0]
	v_pk_fma_f32 v[120:121], v[120:121], 0.5, v[128:129] op_sel_hi:[1,0,1]
	s_waitcnt vmcnt(4)
	v_lshlrev_b32_e32 v128, 16, v150
	v_and_b32_e32 v129, 0xffff0000, v150
	v_pk_fma_f32 v[126:127], v[126:127], 0.5, v[130:131] op_sel_hi:[1,0,1]
	v_pk_mul_f32 v[130:131], v[134:135], s[28:29] op_sel_hi:[1,0]
	v_lshlrev_b32_e32 v132, 16, v152
	v_and_b32_e32 v133, 0xffff0000, v152
	v_pk_mul_f32 v[128:129], v[128:129], s[28:29] op_sel_hi:[1,0]
	v_pk_fma_f32 v[122:123], v[122:123], 0.5, v[130:131] op_sel_hi:[1,0,1]
	v_lshlrev_b32_e32 v130, 16, v151
	v_and_b32_e32 v131, 0xffff0000, v151
	v_pk_fma_f32 v[44:45], v[44:45], 0.5, v[128:129] op_sel_hi:[1,0,1]
	v_pk_mul_f32 v[128:129], v[132:133], s[28:29] op_sel_hi:[1,0]
	v_lshlrev_b32_e32 v134, 16, v153
	v_and_b32_e32 v135, 0xffff0000, v153
	v_pk_mul_f32 v[130:131], v[130:131], s[28:29] op_sel_hi:[1,0]
	v_pk_fma_f32 v[40:41], v[40:41], 0.5, v[128:129] op_sel_hi:[1,0,1]
	s_waitcnt vmcnt(3)
	v_lshlrev_b32_e32 v128, 16, v154
	v_and_b32_e32 v129, 0xffff0000, v154
	v_pk_fma_f32 v[46:47], v[46:47], 0.5, v[130:131] op_sel_hi:[1,0,1]
	v_pk_mul_f32 v[130:131], v[134:135], s[28:29] op_sel_hi:[1,0]
	v_lshlrev_b32_e32 v136, 16, v156
	v_and_b32_e32 v137, 0xffff0000, v156
	v_pk_mul_f32 v[128:129], v[128:129], s[28:29] op_sel_hi:[1,0]
	v_pk_fma_f32 v[42:43], v[42:43], 0.5, v[130:131] op_sel_hi:[1,0,1]
	v_lshlrev_b32_e32 v130, 16, v155
	v_and_b32_e32 v131, 0xffff0000, v155
	v_pk_fma_f32 v[132:133], v[76:77], 0.5, v[128:129] op_sel_hi:[1,0,1]
	v_pk_mul_f32 v[76:77], v[136:137], s[28:29] op_sel_hi:[1,0]
	v_lshlrev_b32_e32 v138, 16, v157
	v_and_b32_e32 v139, 0xffff0000, v157
	v_pk_mul_f32 v[130:131], v[130:131], s[28:29] op_sel_hi:[1,0]
	v_pk_fma_f32 v[128:129], v[72:73], 0.5, v[76:77] op_sel_hi:[1,0,1]
	s_waitcnt vmcnt(1)
	v_lshlrev_b32_e32 v72, 16, v192
	v_and_b32_e32 v73, 0xffff0000, v192
	v_pk_fma_f32 v[134:135], v[78:79], 0.5, v[130:131] op_sel_hi:[1,0,1]
	v_pk_mul_f32 v[78:79], v[138:139], s[28:29] op_sel_hi:[1,0]
	v_lshlrev_b32_e32 v76, 16, v194
	v_and_b32_e32 v77, 0xffff0000, v194
	v_pk_mul_f32 v[72:73], v[72:73], s[28:29] op_sel_hi:[1,0]
	v_pk_fma_f32 v[130:131], v[74:75], 0.5, v[78:79] op_sel_hi:[1,0,1]
	v_lshlrev_b32_e32 v74, 16, v193
	v_and_b32_e32 v75, 0xffff0000, v193
	v_pk_fma_f32 v[52:53], v[52:53], 0.5, v[72:73] op_sel_hi:[1,0,1]
	v_pk_mul_f32 v[72:73], v[76:77], s[28:29] op_sel_hi:[1,0]
	v_lshlrev_b32_e32 v78, 16, v195
	v_and_b32_e32 v79, 0xffff0000, v195
	v_pk_mul_f32 v[74:75], v[74:75], s[28:29] op_sel_hi:[1,0]
	v_pk_fma_f32 v[48:49], v[48:49], 0.5, v[72:73] op_sel_hi:[1,0,1]
	v_lshlrev_b32_e32 v72, 16, v188
	v_and_b32_e32 v73, 0xffff0000, v188
	v_pk_fma_f32 v[54:55], v[54:55], 0.5, v[74:75] op_sel_hi:[1,0,1]
	v_pk_mul_f32 v[74:75], v[78:79], s[28:29] op_sel_hi:[1,0]
	v_lshlrev_b32_e32 v76, 16, v190
	v_and_b32_e32 v77, 0xffff0000, v190
	v_pk_mul_f32 v[72:73], v[72:73], s[28:29] op_sel_hi:[1,0]
	v_pk_fma_f32 v[50:51], v[50:51], 0.5, v[74:75] op_sel_hi:[1,0,1]
	v_lshlrev_b32_e32 v74, 16, v189
	v_and_b32_e32 v75, 0xffff0000, v189
	v_pk_fma_f32 v[140:141], v[68:69], 0.5, v[72:73] op_sel_hi:[1,0,1]
	v_pk_mul_f32 v[68:69], v[76:77], s[28:29] op_sel_hi:[1,0]
	v_lshlrev_b32_e32 v78, 16, v191
	v_and_b32_e32 v79, 0xffff0000, v191
	v_pk_mul_f32 v[74:75], v[74:75], s[28:29] op_sel_hi:[1,0]
	v_pk_fma_f32 v[136:137], v[64:65], 0.5, v[68:69] op_sel_hi:[1,0,1]
	s_waitcnt vmcnt(0)
	v_lshlrev_b32_e32 v64, 16, v144
	v_and_b32_e32 v65, 0xffff0000, v144
	v_pk_fma_f32 v[142:143], v[70:71], 0.5, v[74:75] op_sel_hi:[1,0,1]
	v_pk_mul_f32 v[70:71], v[78:79], s[28:29] op_sel_hi:[1,0]
	v_lshlrev_b32_e32 v68, 16, v146
	v_and_b32_e32 v69, 0xffff0000, v146
	v_pk_mul_f32 v[64:65], v[64:65], s[28:29] op_sel_hi:[1,0]
	v_pk_fma_f32 v[138:139], v[66:67], 0.5, v[70:71] op_sel_hi:[1,0,1]
	v_lshlrev_b32_e32 v66, 16, v145
	v_and_b32_e32 v67, 0xffff0000, v145
	v_pk_fma_f32 v[60:61], v[60:61], 0.5, v[64:65] op_sel_hi:[1,0,1]
	v_pk_mul_f32 v[64:65], v[68:69], s[28:29] op_sel_hi:[1,0]
	v_lshlrev_b32_e32 v70, 16, v147
	v_and_b32_e32 v71, 0xffff0000, v147
	v_pk_mul_f32 v[66:67], v[66:67], s[28:29] op_sel_hi:[1,0]
	v_pk_fma_f32 v[56:57], v[56:57], 0.5, v[64:65] op_sel_hi:[1,0,1]
	v_add_u32_e32 v64, s6, v148
	v_pk_fma_f32 v[62:63], v[62:63], 0.5, v[66:67] op_sel_hi:[1,0,1]
	v_pk_mul_f32 v[66:67], v[70:71], s[28:29] op_sel_hi:[1,0]
	v_ashrrev_i32_e32 v65, 31, v64
	v_pk_fma_f32 v[58:59], v[58:59], 0.5, v[66:67] op_sel_hi:[1,0,1]
	v_lshlrev_b64 v[64:65], 2, v[64:65]
	v_lshl_add_u64 v[68:69], s[20:21], 0, v[64:65]
	v_lshl_add_u64 v[76:77], s[22:23], 0, v[64:65]
	global_load_dwordx4 v[144:147], v[68:69], off offset:16
	global_load_dwordx4 v[152:155], v[68:69], off
	global_load_dwordx4 v[148:151], v[76:77], off offset:16
	global_load_dwordx4 v[156:159], v[76:77], off
	global_load_dwordx4 v[64:67], v[68:69], off offset:528
	global_load_dwordx4 v[72:75], v[68:69], off offset:512
	s_nop 0
	global_load_dwordx4 v[68:71], v[76:77], off offset:528
	s_nop 0
	global_load_dwordx4 v[76:79], v[76:77], off offset:512
	v_pk_add_f32 v[188:189], v[92:93], v[88:89]
	v_pk_add_f32 v[190:191], v[14:15], v[10:11]
	v_pk_add_f32 v[192:193], v[12:13], v[8:9]
	v_pk_add_f32 v[174:175], v[174:175], v[190:191]
	v_pk_add_f32 v[188:189], v[188:189], v[192:193]
	v_add_f32_e32 v174, v174, v175
	v_add_f32_e32 v188, v188, v189
	v_add_f32_e32 v174, v188, v174
	v_mov_b32_e32 v175, v174
	s_nop 1
	v_permlane16_swap_b32_e32 v174, v175
	v_add_f32_e32 v174, v174, v175
	v_mov_b32_e32 v175, v174
	s_nop 1
	v_permlane32_swap_b32_e32 v174, v175
	v_add_f32_e32 v174, v174, v175
	v_fmamk_f32 v193, v174, 0xbc800000, v89
	v_fmamk_f32 v192, v174, 0xbc800000, v88
	v_fmamk_f32 v195, v174, 0xbc800000, v91
	v_fmamk_f32 v194, v174, 0xbc800000, v90
	v_fmamk_f32 v189, v174, 0xbc800000, v95
	v_fmamk_f32 v188, v174, 0xbc800000, v94
	v_fmamk_f32 v191, v174, 0xbc800000, v93
	v_fmamk_f32 v190, v174, 0xbc800000, v92
	v_fmamk_f32 v201, v174, 0xbc800000, v9
	v_fmamk_f32 v200, v174, 0xbc800000, v8
	v_fmamk_f32 v203, v174, 0xbc800000, v11
	v_fmamk_f32 v202, v174, 0xbc800000, v10
	v_pk_mul_f32 v[194:195], v[194:195], v[194:195]
	v_pk_mul_f32 v[192:193], v[192:193], v[192:193]
	v_fmamk_f32 v197, v174, 0xbc800000, v15
	v_fmamk_f32 v196, v174, 0xbc800000, v14
	v_fmamk_f32 v199, v174, 0xbc800000, v13
	v_fmamk_f32 v198, v174, 0xbc800000, v12
	v_pk_fma_f32 v[190:191], v[190:191], v[190:191], v[192:193]
	v_pk_fma_f32 v[188:189], v[188:189], v[188:189], v[194:195]
	v_pk_mul_f32 v[192:193], v[202:203], v[202:203]
	v_pk_mul_f32 v[194:195], v[200:201], v[200:201]
	v_pk_fma_f32 v[192:193], v[196:197], v[196:197], v[192:193]
	v_pk_fma_f32 v[194:195], v[198:199], v[198:199], v[194:195]
	v_pk_add_f32 v[188:189], v[188:189], v[192:193]
	v_pk_add_f32 v[190:191], v[190:191], v[194:195]
	v_add_f32_e32 v188, v188, v189
	v_add_f32_e32 v175, v190, v191
	v_add_f32_e32 v175, v175, v188
	v_mov_b32_e32 v188, v175
	s_nop 1
	v_permlane16_swap_b32_e32 v175, v188
	s_lshl_b32 s6, s8, 3
	v_add_f32_e32 v175, v175, v188
	s_add_i32 s11, s6, 0
	v_mov_b32_e32 v188, v175
	s_add_i32 s11, s11, 0x21000
	s_nop 0
	v_permlane32_swap_b32_e32 v175, v188
	s_and_saveexec_b64 s[6:7], vcc
	s_cbranch_execz .LBB0_1905
	s_lshl_b32 s15, s9, 11
	s_add_i32 s15, s11, s15
	v_mul_f32_e32 v174, 0x3c800000, v174
	v_lshl_add_u32 v189, v186, 5, s15
	v_add_f32_e32 v175, v175, v188
	ds_write_b64 v189, v[174:175]

.LBB0_2545:
	v_mov_b32_e32 v186, v177
	s_mov_b32 s6, s4
	v_mov_b32_e32 v187, v178
	s_mov_b32 s7, s54
	s_lshl_b32 s1, s12, 2
	s_ashr_i32 s8, s7, 1
	s_lshl_b32 s29, s6, 6
	s_add_i32 s36, s8, s1
	s_lshl_b32 s8, s38, 8
	s_lshl_b32 s0, s7, 5
	s_ashr_i32 s37, s36, 31
	s_add_i32 s75, s29, s8
	v_add_u32_e32 v128, s75, v186
	s_and_b32 s1, s0, 32
	s_lshl_b64 s[36:37], s[36:37], 22
	v_ashrrev_i32_e32 v129, 31, v128
	s_add_u32 s36, s58, s36
	v_lshlrev_b64 v[128:129], 7, v[128:129]
	s_addc_u32 s37, s59, s37
	v_lshlrev_b32_e32 v144, 3, v187
	v_lshl_add_u64 v[128:129], s[36:37], 0, v[128:129]
	s_lshl_b32 s10, s1, 1
	v_ashrrev_i32_e32 v145, 31, v144
	v_lshl_add_u64 v[128:129], v[128:129], 0, s[10:11]
	v_lshl_add_u64 v[132:133], v[144:145], 1, v[128:129]
	v_add_co_u32_e32 v128, vcc, s68, v132
	global_load_dwordx4 v[134:137], v[132:133], off nt
	global_load_dwordx4 v[138:141], v[132:133], off offset:2048 nt
	v_addc_co_u32_e32 v129, vcc, 0, v133, vcc
	v_add_co_u32_e32 v130, vcc, s66, v132
	global_load_dwordx4 v[146:149], v[128:129], off offset:-4096 nt
	s_nop 0
	v_addc_co_u32_e32 v131, vcc, 0, v133, vcc
	global_load_dwordx4 v[150:153], v[130:131], off offset:2048 nt
	v_add_co_u32_e32 v130, vcc, s67, v132
	s_lshl_b32 s1, s12, 8
	s_nop 0
	v_addc_co_u32_e32 v131, vcc, 0, v133, vcc
	global_load_dwordx4 v[154:157], v[130:131], off nt
	global_load_dwordx4 v[188:191], v[128:129], off nt
	global_load_dwordx4 v[192:195], v[130:131], off offset:2048 nt
	s_nop 0
	global_load_dwordx4 v[128:131], v[128:129], off offset:2048 nt
	s_add_i32 s0, s0, s1
	s_waitcnt vmcnt(0)
	v_lshlrev_b32_e32 v142, 16, v134
	v_and_b32_e32 v143, 0xffff0000, v134
	v_lshlrev_b32_e32 v134, 16, v135
	v_and_b32_e32 v135, 0xffff0000, v135
	v_lshlrev_b32_e32 v158, 16, v136
	v_and_b32_e32 v159, 0xffff0000, v136
	v_lshlrev_b32_e32 v136, 16, v137
	v_and_b32_e32 v137, 0xffff0000, v137
	v_lshlrev_b32_e32 v174, 16, v138
	v_and_b32_e32 v175, 0xffff0000, v138
	v_lshlrev_b32_e32 v138, 16, v139
	v_and_b32_e32 v139, 0xffff0000, v139
	v_lshlrev_b32_e32 v196, 16, v140
	v_and_b32_e32 v197, 0xffff0000, v140
	v_lshlrev_b32_e32 v140, 16, v141
	v_and_b32_e32 v141, 0xffff0000, v141
	v_pk_fma_f32 v[106:107], v[134:135], s[26:27], v[106:107] op_sel_hi:[1,0,1]
	v_pk_fma_f32 v[98:99], v[136:137], s[26:27], v[98:99] op_sel_hi:[1,0,1]
	v_lshlrev_b32_e32 v134, 16, v146
	v_and_b32_e32 v135, 0xffff0000, v146
	v_lshlrev_b32_e32 v136, 16, v147
	v_and_b32_e32 v137, 0xffff0000, v147
	v_pk_fma_f32 v[86:87], v[138:139], s[26:27], v[86:87] op_sel_hi:[1,0,1]
	v_pk_fma_f32 v[82:83], v[140:141], s[26:27], v[82:83] op_sel_hi:[1,0,1]
	v_lshlrev_b32_e32 v138, 16, v150
	v_and_b32_e32 v139, 0xffff0000, v150
	v_lshlrev_b32_e32 v140, 16, v151
	v_and_b32_e32 v141, 0xffff0000, v151
	v_pk_fma_f32 v[30:31], v[136:137], s[26:27], v[30:31] op_sel_hi:[1,0,1]
	v_pk_fma_f32 v[28:29], v[134:135], s[26:27], v[28:29] op_sel_hi:[1,0,1]
	v_lshlrev_b32_e32 v134, 16, v154
	v_and_b32_e32 v135, 0xffff0000, v154
	v_lshlrev_b32_e32 v136, 16, v155
	v_and_b32_e32 v137, 0xffff0000, v155
	v_pk_fma_f32 v[104:105], v[142:143], s[26:27], v[104:105] op_sel_hi:[1,0,1]
	v_lshlrev_b32_e32 v142, 16, v148
	v_and_b32_e32 v143, 0xffff0000, v148
	v_pk_fma_f32 v[6:7], v[140:141], s[26:27], v[6:7] op_sel_hi:[1,0,1]
	v_pk_fma_f32 v[4:5], v[138:139], s[26:27], v[4:5] op_sel_hi:[1,0,1]
	v_lshlrev_b32_e32 v138, 16, v156
	v_and_b32_e32 v139, 0xffff0000, v156
	v_lshlrev_b32_e32 v140, 16, v157
	v_and_b32_e32 v141, 0xffff0000, v157
	v_pk_fma_f32 v[94:95], v[136:137], s[26:27], v[94:95] op_sel_hi:[1,0,1]
	v_pk_fma_f32 v[92:93], v[134:135], s[26:27], v[92:93] op_sel_hi:[1,0,1]
	v_lshlrev_b32_e32 v134, 16, v188
	v_and_b32_e32 v135, 0xffff0000, v188
	v_lshlrev_b32_e32 v136, 16, v189
	v_and_b32_e32 v137, 0xffff0000, v189
	v_pk_fma_f32 v[16:17], v[142:143], s[26:27], v[16:17] op_sel_hi:[1,0,1]
	v_pk_fma_f32 v[90:91], v[140:141], s[26:27], v[90:91] op_sel_hi:[1,0,1]
	v_pk_fma_f32 v[88:89], v[138:139], s[26:27], v[88:89] op_sel_hi:[1,0,1]
	v_lshlrev_b32_e32 v138, 16, v190
	v_and_b32_e32 v139, 0xffff0000, v190
	v_lshlrev_b32_e32 v140, 16, v191
	v_and_b32_e32 v141, 0xffff0000, v191
	v_pk_fma_f32 v[14:15], v[136:137], s[26:27], v[14:15] op_sel_hi:[1,0,1]
	v_pk_fma_f32 v[12:13], v[134:135], s[26:27], v[12:13] op_sel_hi:[1,0,1]
	v_lshlrev_b32_e32 v134, 16, v192
	v_and_b32_e32 v135, 0xffff0000, v192
	v_lshlrev_b32_e32 v136, 16, v193
	v_and_b32_e32 v137, 0xffff0000, v193
	v_add_co_u32_e32 v142, vcc, s70, v132
	v_lshlrev_b32_e32 v146, 16, v149
	v_and_b32_e32 v147, 0xffff0000, v149
	v_lshlrev_b32_e32 v148, 16, v152
	v_and_b32_e32 v149, 0xffff0000, v152
	v_lshlrev_b32_e32 v150, 16, v153
	v_and_b32_e32 v151, 0xffff0000, v153
	v_pk_fma_f32 v[10:11], v[140:141], s[26:27], v[10:11] op_sel_hi:[1,0,1]
	v_pk_fma_f32 v[8:9], v[138:139], s[26:27], v[8:9] op_sel_hi:[1,0,1]
	v_lshlrev_b32_e32 v138, 16, v194
	v_and_b32_e32 v139, 0xffff0000, v194
	v_lshlrev_b32_e32 v140, 16, v195
	v_and_b32_e32 v141, 0xffff0000, v195
	v_pk_fma_f32 v[110:111], v[136:137], s[26:27], v[110:111] op_sel_hi:[1,0,1]
	v_pk_fma_f32 v[108:109], v[134:135], s[26:27], v[108:109] op_sel_hi:[1,0,1]
	v_lshlrev_b32_e32 v134, 16, v128
	v_and_b32_e32 v135, 0xffff0000, v128
	v_lshlrev_b32_e32 v128, 16, v129
	v_and_b32_e32 v129, 0xffff0000, v129
	v_lshlrev_b32_e32 v136, 16, v130
	v_and_b32_e32 v137, 0xffff0000, v130
	v_lshlrev_b32_e32 v130, 16, v131
	v_and_b32_e32 v131, 0xffff0000, v131
	v_addc_co_u32_e32 v143, vcc, 0, v133, vcc
	v_pk_fma_f32 v[96:97], v[158:159], s[26:27], v[96:97] op_sel_hi:[1,0,1]
	v_pk_fma_f32 v[84:85], v[174:175], s[26:27], v[84:85] op_sel_hi:[1,0,1]
	v_pk_fma_f32 v[80:81], v[196:197], s[26:27], v[80:81] op_sel_hi:[1,0,1]
	v_pk_fma_f32 v[18:19], v[146:147], s[26:27], v[18:19] op_sel_hi:[1,0,1]
	v_pk_fma_f32 v[2:3], v[150:151], s[26:27], v[2:3] op_sel_hi:[1,0,1]
	v_pk_fma_f32 v[0:1], v[148:149], s[26:27], v[0:1] op_sel_hi:[1,0,1]
	v_pk_fma_f32 v[102:103], v[140:141], s[26:27], v[102:103] op_sel_hi:[1,0,1]
	v_pk_fma_f32 v[100:101], v[138:139], s[26:27], v[100:101] op_sel_hi:[1,0,1]
	v_pk_fma_f32 v[26:27], v[128:129], s[26:27], v[26:27] op_sel_hi:[1,0,1]
	v_pk_fma_f32 v[24:25], v[134:135], s[26:27], v[24:25] op_sel_hi:[1,0,1]
	v_pk_fma_f32 v[22:23], v[130:131], s[26:27], v[22:23] op_sel_hi:[1,0,1]
	v_pk_fma_f32 v[20:21], v[136:137], s[26:27], v[20:21] op_sel_hi:[1,0,1]
	v_add_co_u32_e32 v158, vcc, s71, v132
	s_nop 1
	v_addc_co_u32_e32 v159, vcc, 0, v133, vcc
	global_load_dwordx4 v[128:131], v[142:143], off offset:-4096 nt
	v_add_co_u32_e32 v138, vcc, s51, v132
	global_load_dwordx4 v[134:137], v[158:159], off offset:-4096 nt
	s_nop 0
	v_addc_co_u32_e32 v139, vcc, 0, v133, vcc
	global_load_dwordx4 v[138:141], v[138:139], off offset:2048 nt
	v_add_co_u32_e32 v132, vcc, s69, v132
	v_pk_add_f32 v[174:175], v[106:107], v[98:99]
	s_nop 0
	v_addc_co_u32_e32 v133, vcc, 0, v133, vcc
	global_load_dwordx4 v[146:149], v[132:133], off offset:2048 nt
	global_load_dwordx4 v[150:153], v[142:143], off nt
	global_load_dwordx4 v[154:157], v[158:159], off nt
	global_load_dwordx4 v[188:191], v[142:143], off offset:2048 nt
	global_load_dwordx4 v[192:195], v[158:159], off offset:2048 nt
	v_cmp_eq_u32_e32 vcc, 0, v187
	s_waitcnt vmcnt(7)
	v_lshlrev_b32_e32 v132, 16, v128
	v_and_b32_e32 v133, 0xffff0000, v128
	v_lshlrev_b32_e32 v128, 16, v129
	v_and_b32_e32 v129, 0xffff0000, v129
	v_pk_fma_f32 v[118:119], v[128:129], s[26:27], v[118:119] op_sel_hi:[1,0,1]
	s_waitcnt vmcnt(6)
	v_lshlrev_b32_e32 v128, 16, v134
	v_and_b32_e32 v129, 0xffff0000, v134
	v_lshlrev_b32_e32 v142, 16, v130
	v_and_b32_e32 v143, 0xffff0000, v130
	v_lshlrev_b32_e32 v130, 16, v131
	v_and_b32_e32 v131, 0xffff0000, v131
	v_pk_fma_f32 v[116:117], v[132:133], s[26:27], v[116:117] op_sel_hi:[1,0,1]
	v_lshlrev_b32_e32 v132, 16, v136
	v_and_b32_e32 v133, 0xffff0000, v136
	v_pk_fma_f32 v[36:37], v[128:129], s[26:27], v[36:37] op_sel_hi:[1,0,1]
	s_waitcnt vmcnt(5)
	v_lshlrev_b32_e32 v128, 16, v138
	v_and_b32_e32 v129, 0xffff0000, v138
	v_pk_fma_f32 v[114:115], v[130:131], s[26:27], v[114:115] op_sel_hi:[1,0,1]
	v_lshlrev_b32_e32 v130, 16, v135
	v_and_b32_e32 v131, 0xffff0000, v135
	v_pk_fma_f32 v[32:33], v[132:133], s[26:27], v[32:33] op_sel_hi:[1,0,1]
	v_lshlrev_b32_e32 v132, 16, v140
	v_and_b32_e32 v133, 0xffff0000, v140
	v_pk_fma_f32 v[124:125], v[128:129], s[26:27], v[124:125] op_sel_hi:[1,0,1]
	s_waitcnt vmcnt(4)
	v_lshlrev_b32_e32 v128, 16, v146
	v_and_b32_e32 v129, 0xffff0000, v146
	v_lshlrev_b32_e32 v134, 16, v137
	v_and_b32_e32 v135, 0xffff0000, v137
	v_pk_fma_f32 v[38:39], v[130:131], s[26:27], v[38:39] op_sel_hi:[1,0,1]
	v_lshlrev_b32_e32 v130, 16, v139
	v_and_b32_e32 v131, 0xffff0000, v139
	v_pk_fma_f32 v[120:121], v[132:133], s[26:27], v[120:121] op_sel_hi:[1,0,1]
	v_lshlrev_b32_e32 v132, 16, v148
	v_and_b32_e32 v133, 0xffff0000, v148
	v_pk_fma_f32 v[44:45], v[128:129], s[26:27], v[44:45] op_sel_hi:[1,0,1]
	s_waitcnt vmcnt(3)
	v_lshlrev_b32_e32 v128, 16, v150
	v_and_b32_e32 v129, 0xffff0000, v150
	v_pk_fma_f32 v[34:35], v[134:135], s[26:27], v[34:35] op_sel_hi:[1,0,1]
	v_lshlrev_b32_e32 v134, 16, v141
	v_and_b32_e32 v135, 0xffff0000, v141
	v_pk_fma_f32 v[126:127], v[130:131], s[26:27], v[126:127] op_sel_hi:[1,0,1]
	v_lshlrev_b32_e32 v130, 16, v147
	v_and_b32_e32 v131, 0xffff0000, v147
	v_pk_fma_f32 v[40:41], v[132:133], s[26:27], v[40:41] op_sel_hi:[1,0,1]
	v_pk_fma_f32 v[132:133], v[128:129], s[26:27], v[76:77] op_sel_hi:[1,0,1]
	s_waitcnt vmcnt(2)
	v_lshlrev_b32_e32 v76, 16, v156
	v_and_b32_e32 v77, 0xffff0000, v156
	v_pk_fma_f32 v[122:123], v[134:135], s[26:27], v[122:123] op_sel_hi:[1,0,1]
	v_lshlrev_b32_e32 v134, 16, v149
	v_and_b32_e32 v135, 0xffff0000, v149
	v_pk_fma_f32 v[46:47], v[130:131], s[26:27], v[46:47] op_sel_hi:[1,0,1]
	v_lshlrev_b32_e32 v130, 16, v151
	v_and_b32_e32 v131, 0xffff0000, v151
	v_lshlrev_b32_e32 v136, 16, v152
	v_and_b32_e32 v137, 0xffff0000, v152
	v_lshlrev_b32_e32 v138, 16, v153
	v_and_b32_e32 v139, 0xffff0000, v153
	v_pk_fma_f32 v[48:49], v[76:77], s[26:27], v[48:49] op_sel_hi:[1,0,1]
	s_waitcnt vmcnt(1)
	v_lshlrev_b32_e32 v76, 16, v190
	v_and_b32_e32 v77, 0xffff0000, v190
	v_pk_fma_f32 v[42:43], v[134:135], s[26:27], v[42:43] op_sel_hi:[1,0,1]
	v_pk_fma_f32 v[134:135], v[130:131], s[26:27], v[78:79] op_sel_hi:[1,0,1]
	v_pk_fma_f32 v[130:131], v[138:139], s[26:27], v[74:75] op_sel_hi:[1,0,1]
	v_pk_fma_f32 v[128:129], v[136:137], s[26:27], v[72:73] op_sel_hi:[1,0,1]
	v_lshlrev_b32_e32 v72, 16, v154
	v_and_b32_e32 v73, 0xffff0000, v154
	v_lshlrev_b32_e32 v74, 16, v155
	v_and_b32_e32 v75, 0xffff0000, v155
	v_lshlrev_b32_e32 v78, 16, v157
	v_and_b32_e32 v79, 0xffff0000, v157
	v_pk_fma_f32 v[136:137], v[76:77], s[26:27], v[64:65] op_sel_hi:[1,0,1]
	s_waitcnt vmcnt(0)
	v_lshlrev_b32_e32 v64, 16, v192
	v_and_b32_e32 v65, 0xffff0000, v192
	v_pk_fma_f32 v[54:55], v[74:75], s[26:27], v[54:55] op_sel_hi:[1,0,1]
	v_pk_fma_f32 v[52:53], v[72:73], s[26:27], v[52:53] op_sel_hi:[1,0,1]
	v_pk_fma_f32 v[50:51], v[78:79], s[26:27], v[50:51] op_sel_hi:[1,0,1]
	v_lshlrev_b32_e32 v72, 16, v188
	v_and_b32_e32 v73, 0xffff0000, v188
	v_lshlrev_b32_e32 v74, 16, v189
	v_and_b32_e32 v75, 0xffff0000, v189
	v_lshlrev_b32_e32 v78, 16, v191
	v_and_b32_e32 v79, 0xffff0000, v191
	v_pk_fma_f32 v[60:61], v[64:65], s[26:27], v[60:61] op_sel_hi:[1,0,1]
	v_add_u32_e32 v64, s0, v144
	v_pk_fma_f32 v[112:113], v[142:143], s[26:27], v[112:113] op_sel_hi:[1,0,1]
	v_pk_fma_f32 v[142:143], v[74:75], s[26:27], v[70:71] op_sel_hi:[1,0,1]
	v_pk_fma_f32 v[140:141], v[72:73], s[26:27], v[68:69] op_sel_hi:[1,0,1]
	v_pk_fma_f32 v[138:139], v[78:79], s[26:27], v[66:67] op_sel_hi:[1,0,1]
	v_lshlrev_b32_e32 v66, 16, v193
	v_and_b32_e32 v67, 0xffff0000, v193
	v_lshlrev_b32_e32 v68, 16, v194
	v_and_b32_e32 v69, 0xffff0000, v194
	v_lshlrev_b32_e32 v70, 16, v195
	v_and_b32_e32 v71, 0xffff0000, v195
	v_ashrrev_i32_e32 v65, 31, v64
	v_pk_fma_f32 v[62:63], v[66:67], s[26:27], v[62:63] op_sel_hi:[1,0,1]
	v_pk_fma_f32 v[58:59], v[70:71], s[26:27], v[58:59] op_sel_hi:[1,0,1]
	v_pk_fma_f32 v[56:57], v[68:69], s[26:27], v[56:57] op_sel_hi:[1,0,1]
	v_lshlrev_b64 v[64:65], 2, v[64:65]
	v_lshl_add_u64 v[68:69], s[18:19], 0, v[64:65]
	v_lshl_add_u64 v[76:77], s[20:21], 0, v[64:65]
	global_load_dwordx4 v[144:147], v[68:69], off offset:16
	global_load_dwordx4 v[152:155], v[68:69], off
	global_load_dwordx4 v[148:151], v[76:77], off offset:16
	global_load_dwordx4 v[156:159], v[76:77], off
	global_load_dwordx4 v[64:67], v[68:69], off offset:528
	global_load_dwordx4 v[72:75], v[68:69], off offset:512
	s_nop 0
	global_load_dwordx4 v[68:71], v[76:77], off offset:528
	s_nop 0
	global_load_dwordx4 v[76:79], v[76:77], off offset:512
	v_pk_add_f32 v[188:189], v[104:105], v[96:97]
	v_pk_add_f32 v[190:191], v[30:31], v[18:19]
	v_pk_add_f32 v[192:193], v[28:29], v[16:17]
	v_pk_add_f32 v[174:175], v[174:175], v[190:191]
	v_pk_add_f32 v[188:189], v[188:189], v[192:193]
	v_add_f32_e32 v174, v174, v175
	v_add_f32_e32 v188, v188, v189
	v_add_f32_e32 v174, v188, v174
	v_mov_b32_e32 v175, v174
	s_nop 1
	v_permlane16_swap_b32_e32 v174, v175
	v_add_f32_e32 v174, v174, v175
	v_mov_b32_e32 v175, v174
	s_nop 1
	v_permlane32_swap_b32_e32 v174, v175
	v_add_f32_e32 v174, v174, v175
	v_fmamk_f32 v193, v174, 0xbc800000, v97
	v_fmamk_f32 v192, v174, 0xbc800000, v96
	v_fmamk_f32 v195, v174, 0xbc800000, v99
	v_fmamk_f32 v194, v174, 0xbc800000, v98
	v_fmamk_f32 v189, v174, 0xbc800000, v107
	v_fmamk_f32 v188, v174, 0xbc800000, v106
	v_fmamk_f32 v191, v174, 0xbc800000, v105
	v_fmamk_f32 v190, v174, 0xbc800000, v104
	v_fmamk_f32 v201, v174, 0xbc800000, v17
	v_fmamk_f32 v200, v174, 0xbc800000, v16
	v_fmamk_f32 v203, v174, 0xbc800000, v19
	v_fmamk_f32 v202, v174, 0xbc800000, v18
	v_pk_mul_f32 v[194:195], v[194:195], v[194:195]
	v_pk_mul_f32 v[192:193], v[192:193], v[192:193]
	v_fmamk_f32 v197, v174, 0xbc800000, v31
	v_fmamk_f32 v196, v174, 0xbc800000, v30
	v_fmamk_f32 v199, v174, 0xbc800000, v29
	v_fmamk_f32 v198, v174, 0xbc800000, v28
	v_pk_fma_f32 v[190:191], v[190:191], v[190:191], v[192:193]
	v_pk_fma_f32 v[188:189], v[188:189], v[188:189], v[194:195]
	v_pk_mul_f32 v[192:193], v[202:203], v[202:203]
	v_pk_mul_f32 v[194:195], v[200:201], v[200:201]
	v_pk_fma_f32 v[192:193], v[196:197], v[196:197], v[192:193]
	v_pk_fma_f32 v[194:195], v[198:199], v[198:199], v[194:195]
	v_pk_add_f32 v[188:189], v[188:189], v[192:193]
	v_pk_add_f32 v[190:191], v[190:191], v[194:195]
	v_add_f32_e32 v188, v188, v189
	v_add_f32_e32 v175, v190, v191
	v_add_f32_e32 v175, v175, v188
	v_mov_b32_e32 v188, v175
	s_nop 1
	v_permlane16_swap_b32_e32 v175, v188
	s_lshl_b32 s0, s7, 3
	v_add_f32_e32 v175, v175, v188
	s_add_i32 s9, s0, 0
	v_mov_b32_e32 v188, v175
	s_add_i32 s9, s9, 0x21000
	s_nop 0
	v_permlane32_swap_b32_e32 v175, v188
	s_and_saveexec_b64 s[0:1], vcc
	s_cbranch_execz .LBB0_2547
	s_lshl_b32 s13, s6, 11
	s_add_i32 s13, s9, s13
	v_mul_f32_e32 v174, 0x3c800000, v174
	v_add_f32_e32 v175, v175, v188
	v_lshl_add_u32 v188, v186, 5, s13
	ds_write_b64 v188, v[174:175]

.LBB0_2775:
	v_mov_b32_e32 v187, v178
	s_mov_b32 s6, s53
	v_mov_b32_e32 v186, v177
	s_mov_b32 s7, s2
	s_lshl_b32 s1, s12, 2
	s_ashr_i32 s8, s6, 1
	s_lshl_b32 s27, s7, 6
	s_add_i32 s36, s8, s1
	s_lshl_b32 s8, s38, 8
	s_lshl_b32 s0, s6, 5
	s_ashr_i32 s37, s36, 31
	s_add_i32 s29, s27, s8
	v_add_u32_e32 v128, s29, v186
	s_and_b32 s1, s0, 32
	s_lshl_b64 s[36:37], s[36:37], 22
	v_ashrrev_i32_e32 v129, 31, v128
	s_add_u32 s36, s58, s36
	v_lshlrev_b64 v[128:129], 7, v[128:129]
	s_addc_u32 s37, s59, s37
	v_lshlrev_b32_e32 v144, 3, v187
	v_lshl_add_u64 v[128:129], s[36:37], 0, v[128:129]
	s_lshl_b32 s10, s1, 1
	v_ashrrev_i32_e32 v145, 31, v144
	v_lshl_add_u64 v[128:129], v[128:129], 0, s[10:11]
	v_lshl_add_u64 v[132:133], v[144:145], 1, v[128:129]
	v_add_co_u32_e32 v128, vcc, s65, v132
	global_load_dwordx4 v[134:137], v[132:133], off nt
	global_load_dwordx4 v[138:141], v[132:133], off offset:2048 nt
	v_addc_co_u32_e32 v129, vcc, 0, v133, vcc
	v_add_co_u32_e32 v130, vcc, s56, v132
	global_load_dwordx4 v[146:149], v[128:129], off offset:-4096 nt
	s_nop 0
	v_addc_co_u32_e32 v131, vcc, 0, v133, vcc
	global_load_dwordx4 v[150:153], v[130:131], off offset:2048 nt
	v_add_co_u32_e32 v130, vcc, s64, v132
	s_lshl_b32 s1, s12, 8
	s_nop 0
	v_addc_co_u32_e32 v131, vcc, 0, v133, vcc
	global_load_dwordx4 v[154:157], v[130:131], off nt
	global_load_dwordx4 v[188:191], v[128:129], off nt
	global_load_dwordx4 v[192:195], v[130:131], off offset:2048 nt
	s_nop 0
	global_load_dwordx4 v[128:131], v[128:129], off offset:2048 nt
	s_add_i32 s0, s0, s1
	s_waitcnt vmcnt(0)
	v_lshlrev_b32_e32 v142, 16, v134
	v_and_b32_e32 v143, 0xffff0000, v134
	v_lshlrev_b32_e32 v134, 16, v135
	v_and_b32_e32 v135, 0xffff0000, v135
	v_lshlrev_b32_e32 v158, 16, v136
	v_and_b32_e32 v159, 0xffff0000, v136
	v_lshlrev_b32_e32 v136, 16, v137
	v_and_b32_e32 v137, 0xffff0000, v137
	v_lshlrev_b32_e32 v174, 16, v138
	v_and_b32_e32 v175, 0xffff0000, v138
	v_lshlrev_b32_e32 v138, 16, v139
	v_and_b32_e32 v139, 0xffff0000, v139
	v_lshlrev_b32_e32 v196, 16, v140
	v_and_b32_e32 v197, 0xffff0000, v140
	v_lshlrev_b32_e32 v140, 16, v141
	v_and_b32_e32 v141, 0xffff0000, v141
	v_pk_fma_f32 v[106:107], v[134:135], s[24:25], v[106:107] op_sel_hi:[1,0,1]
	v_pk_fma_f32 v[98:99], v[136:137], s[24:25], v[98:99] op_sel_hi:[1,0,1]
	v_lshlrev_b32_e32 v134, 16, v146
	v_and_b32_e32 v135, 0xffff0000, v146
	v_lshlrev_b32_e32 v136, 16, v147
	v_and_b32_e32 v137, 0xffff0000, v147
	v_pk_fma_f32 v[86:87], v[138:139], s[24:25], v[86:87] op_sel_hi:[1,0,1]
	v_pk_fma_f32 v[82:83], v[140:141], s[24:25], v[82:83] op_sel_hi:[1,0,1]
	v_lshlrev_b32_e32 v138, 16, v150
	v_and_b32_e32 v139, 0xffff0000, v150
	v_lshlrev_b32_e32 v140, 16, v151
	v_and_b32_e32 v141, 0xffff0000, v151
	v_pk_fma_f32 v[30:31], v[136:137], s[24:25], v[30:31] op_sel_hi:[1,0,1]
	v_pk_fma_f32 v[28:29], v[134:135], s[24:25], v[28:29] op_sel_hi:[1,0,1]
	v_lshlrev_b32_e32 v134, 16, v154
	v_and_b32_e32 v135, 0xffff0000, v154
	v_lshlrev_b32_e32 v136, 16, v155
	v_and_b32_e32 v137, 0xffff0000, v155
	v_pk_fma_f32 v[104:105], v[142:143], s[24:25], v[104:105] op_sel_hi:[1,0,1]
	v_lshlrev_b32_e32 v142, 16, v148
	v_and_b32_e32 v143, 0xffff0000, v148
	v_pk_fma_f32 v[6:7], v[140:141], s[24:25], v[6:7] op_sel_hi:[1,0,1]
	v_pk_fma_f32 v[4:5], v[138:139], s[24:25], v[4:5] op_sel_hi:[1,0,1]
	v_lshlrev_b32_e32 v138, 16, v156
	v_and_b32_e32 v139, 0xffff0000, v156
	v_lshlrev_b32_e32 v140, 16, v157
	v_and_b32_e32 v141, 0xffff0000, v157
	v_pk_fma_f32 v[94:95], v[136:137], s[24:25], v[94:95] op_sel_hi:[1,0,1]
	v_pk_fma_f32 v[92:93], v[134:135], s[24:25], v[92:93] op_sel_hi:[1,0,1]
	v_lshlrev_b32_e32 v134, 16, v188
	v_and_b32_e32 v135, 0xffff0000, v188
	v_lshlrev_b32_e32 v136, 16, v189
	v_and_b32_e32 v137, 0xffff0000, v189
	v_pk_fma_f32 v[16:17], v[142:143], s[24:25], v[16:17] op_sel_hi:[1,0,1]
	v_pk_fma_f32 v[90:91], v[140:141], s[24:25], v[90:91] op_sel_hi:[1,0,1]
	v_pk_fma_f32 v[88:89], v[138:139], s[24:25], v[88:89] op_sel_hi:[1,0,1]
	v_lshlrev_b32_e32 v138, 16, v190
	v_and_b32_e32 v139, 0xffff0000, v190
	v_lshlrev_b32_e32 v140, 16, v191
	v_and_b32_e32 v141, 0xffff0000, v191
	v_pk_fma_f32 v[14:15], v[136:137], s[24:25], v[14:15] op_sel_hi:[1,0,1]
	v_pk_fma_f32 v[12:13], v[134:135], s[24:25], v[12:13] op_sel_hi:[1,0,1]
	v_lshlrev_b32_e32 v134, 16, v192
	v_and_b32_e32 v135, 0xffff0000, v192
	v_lshlrev_b32_e32 v136, 16, v193
	v_and_b32_e32 v137, 0xffff0000, v193
	v_add_co_u32_e32 v142, vcc, s67, v132
	v_lshlrev_b32_e32 v146, 16, v149
	v_and_b32_e32 v147, 0xffff0000, v149
	v_lshlrev_b32_e32 v148, 16, v152
	v_and_b32_e32 v149, 0xffff0000, v152
	v_lshlrev_b32_e32 v150, 16, v153
	v_and_b32_e32 v151, 0xffff0000, v153
	v_pk_fma_f32 v[10:11], v[140:141], s[24:25], v[10:11] op_sel_hi:[1,0,1]
	v_pk_fma_f32 v[8:9], v[138:139], s[24:25], v[8:9] op_sel_hi:[1,0,1]
	v_lshlrev_b32_e32 v138, 16, v194
	v_and_b32_e32 v139, 0xffff0000, v194
	v_lshlrev_b32_e32 v140, 16, v195
	v_and_b32_e32 v141, 0xffff0000, v195
	v_pk_fma_f32 v[110:111], v[136:137], s[24:25], v[110:111] op_sel_hi:[1,0,1]
	v_pk_fma_f32 v[108:109], v[134:135], s[24:25], v[108:109] op_sel_hi:[1,0,1]
	v_lshlrev_b32_e32 v134, 16, v128
	v_and_b32_e32 v135, 0xffff0000, v128
	v_lshlrev_b32_e32 v128, 16, v129
	v_and_b32_e32 v129, 0xffff0000, v129
	v_lshlrev_b32_e32 v136, 16, v130
	v_and_b32_e32 v137, 0xffff0000, v130
	v_lshlrev_b32_e32 v130, 16, v131
	v_and_b32_e32 v131, 0xffff0000, v131
	v_addc_co_u32_e32 v143, vcc, 0, v133, vcc
	v_pk_fma_f32 v[96:97], v[158:159], s[24:25], v[96:97] op_sel_hi:[1,0,1]
	v_pk_fma_f32 v[84:85], v[174:175], s[24:25], v[84:85] op_sel_hi:[1,0,1]
	v_pk_fma_f32 v[80:81], v[196:197], s[24:25], v[80:81] op_sel_hi:[1,0,1]
	v_pk_fma_f32 v[18:19], v[146:147], s[24:25], v[18:19] op_sel_hi:[1,0,1]
	v_pk_fma_f32 v[2:3], v[150:151], s[24:25], v[2:3] op_sel_hi:[1,0,1]
	v_pk_fma_f32 v[0:1], v[148:149], s[24:25], v[0:1] op_sel_hi:[1,0,1]
	v_pk_fma_f32 v[102:103], v[140:141], s[24:25], v[102:103] op_sel_hi:[1,0,1]
	v_pk_fma_f32 v[100:101], v[138:139], s[24:25], v[100:101] op_sel_hi:[1,0,1]
	v_pk_fma_f32 v[26:27], v[128:129], s[24:25], v[26:27] op_sel_hi:[1,0,1]
	v_pk_fma_f32 v[24:25], v[134:135], s[24:25], v[24:25] op_sel_hi:[1,0,1]
	v_pk_fma_f32 v[22:23], v[130:131], s[24:25], v[22:23] op_sel_hi:[1,0,1]
	v_pk_fma_f32 v[20:21], v[136:137], s[24:25], v[20:21] op_sel_hi:[1,0,1]
	v_add_co_u32_e32 v158, vcc, s68, v132
	s_nop 1
	v_addc_co_u32_e32 v159, vcc, 0, v133, vcc
	global_load_dwordx4 v[128:131], v[142:143], off offset:-4096 nt
	v_add_co_u32_e32 v138, vcc, s50, v132
	global_load_dwordx4 v[134:137], v[158:159], off offset:-4096 nt
	s_nop 0
	v_addc_co_u32_e32 v139, vcc, 0, v133, vcc
	global_load_dwordx4 v[138:141], v[138:139], off offset:2048 nt
	v_add_co_u32_e32 v132, vcc, s66, v132
	v_pk_add_f32 v[174:175], v[106:107], v[98:99]
	s_nop 0
	v_addc_co_u32_e32 v133, vcc, 0, v133, vcc
	global_load_dwordx4 v[146:149], v[132:133], off offset:2048 nt
	global_load_dwordx4 v[150:153], v[142:143], off nt
	global_load_dwordx4 v[154:157], v[158:159], off nt
	global_load_dwordx4 v[188:191], v[142:143], off offset:2048 nt
	global_load_dwordx4 v[192:195], v[158:159], off offset:2048 nt
	v_cmp_eq_u32_e32 vcc, 0, v187
	s_waitcnt vmcnt(7)
	v_lshlrev_b32_e32 v132, 16, v128
	v_and_b32_e32 v133, 0xffff0000, v128
	v_lshlrev_b32_e32 v128, 16, v129
	v_and_b32_e32 v129, 0xffff0000, v129
	v_pk_fma_f32 v[118:119], v[128:129], s[24:25], v[118:119] op_sel_hi:[1,0,1]
	s_waitcnt vmcnt(6)
	v_lshlrev_b32_e32 v128, 16, v134
	v_and_b32_e32 v129, 0xffff0000, v134
	v_lshlrev_b32_e32 v142, 16, v130
	v_and_b32_e32 v143, 0xffff0000, v130
	v_lshlrev_b32_e32 v130, 16, v131
	v_and_b32_e32 v131, 0xffff0000, v131
	v_pk_fma_f32 v[116:117], v[132:133], s[24:25], v[116:117] op_sel_hi:[1,0,1]
	v_lshlrev_b32_e32 v132, 16, v136
	v_and_b32_e32 v133, 0xffff0000, v136
	v_pk_fma_f32 v[36:37], v[128:129], s[24:25], v[36:37] op_sel_hi:[1,0,1]
	s_waitcnt vmcnt(5)
	v_lshlrev_b32_e32 v128, 16, v138
	v_and_b32_e32 v129, 0xffff0000, v138
	v_pk_fma_f32 v[114:115], v[130:131], s[24:25], v[114:115] op_sel_hi:[1,0,1]
	v_lshlrev_b32_e32 v130, 16, v135
	v_and_b32_e32 v131, 0xffff0000, v135
	v_pk_fma_f32 v[32:33], v[132:133], s[24:25], v[32:33] op_sel_hi:[1,0,1]
	v_lshlrev_b32_e32 v132, 16, v140
	v_and_b32_e32 v133, 0xffff0000, v140
	v_pk_fma_f32 v[124:125], v[128:129], s[24:25], v[124:125] op_sel_hi:[1,0,1]
	s_waitcnt vmcnt(4)
	v_lshlrev_b32_e32 v128, 16, v146
	v_and_b32_e32 v129, 0xffff0000, v146
	v_lshlrev_b32_e32 v134, 16, v137
	v_and_b32_e32 v135, 0xffff0000, v137
	v_pk_fma_f32 v[38:39], v[130:131], s[24:25], v[38:39] op_sel_hi:[1,0,1]
	v_lshlrev_b32_e32 v130, 16, v139
	v_and_b32_e32 v131, 0xffff0000, v139
	v_pk_fma_f32 v[120:121], v[132:133], s[24:25], v[120:121] op_sel_hi:[1,0,1]
	v_lshlrev_b32_e32 v132, 16, v148
	v_and_b32_e32 v133, 0xffff0000, v148
	v_pk_fma_f32 v[44:45], v[128:129], s[24:25], v[44:45] op_sel_hi:[1,0,1]
	s_waitcnt vmcnt(3)
	v_lshlrev_b32_e32 v128, 16, v150
	v_and_b32_e32 v129, 0xffff0000, v150
	v_pk_fma_f32 v[34:35], v[134:135], s[24:25], v[34:35] op_sel_hi:[1,0,1]
	v_lshlrev_b32_e32 v134, 16, v141
	v_and_b32_e32 v135, 0xffff0000, v141
	v_pk_fma_f32 v[126:127], v[130:131], s[24:25], v[126:127] op_sel_hi:[1,0,1]
	v_lshlrev_b32_e32 v130, 16, v147
	v_and_b32_e32 v131, 0xffff0000, v147
	v_pk_fma_f32 v[40:41], v[132:133], s[24:25], v[40:41] op_sel_hi:[1,0,1]
	v_pk_fma_f32 v[132:133], v[128:129], s[24:25], v[76:77] op_sel_hi:[1,0,1]
	s_waitcnt vmcnt(2)
	v_lshlrev_b32_e32 v76, 16, v156
	v_and_b32_e32 v77, 0xffff0000, v156
	v_pk_fma_f32 v[122:123], v[134:135], s[24:25], v[122:123] op_sel_hi:[1,0,1]
	v_lshlrev_b32_e32 v134, 16, v149
	v_and_b32_e32 v135, 0xffff0000, v149
	v_pk_fma_f32 v[46:47], v[130:131], s[24:25], v[46:47] op_sel_hi:[1,0,1]
	v_lshlrev_b32_e32 v130, 16, v151
	v_and_b32_e32 v131, 0xffff0000, v151
	v_lshlrev_b32_e32 v136, 16, v152
	v_and_b32_e32 v137, 0xffff0000, v152
	v_lshlrev_b32_e32 v138, 16, v153
	v_and_b32_e32 v139, 0xffff0000, v153
	v_pk_fma_f32 v[48:49], v[76:77], s[24:25], v[48:49] op_sel_hi:[1,0,1]
	s_waitcnt vmcnt(1)
	v_lshlrev_b32_e32 v76, 16, v190
	v_and_b32_e32 v77, 0xffff0000, v190
	v_pk_fma_f32 v[42:43], v[134:135], s[24:25], v[42:43] op_sel_hi:[1,0,1]
	v_pk_fma_f32 v[134:135], v[130:131], s[24:25], v[78:79] op_sel_hi:[1,0,1]
	v_pk_fma_f32 v[130:131], v[138:139], s[24:25], v[74:75] op_sel_hi:[1,0,1]
	v_pk_fma_f32 v[128:129], v[136:137], s[24:25], v[72:73] op_sel_hi:[1,0,1]
	v_lshlrev_b32_e32 v72, 16, v154
	v_and_b32_e32 v73, 0xffff0000, v154
	v_lshlrev_b32_e32 v74, 16, v155
	v_and_b32_e32 v75, 0xffff0000, v155
	v_lshlrev_b32_e32 v78, 16, v157
	v_and_b32_e32 v79, 0xffff0000, v157
	v_pk_fma_f32 v[136:137], v[76:77], s[24:25], v[64:65] op_sel_hi:[1,0,1]
	s_waitcnt vmcnt(0)
	v_lshlrev_b32_e32 v64, 16, v192
	v_and_b32_e32 v65, 0xffff0000, v192
	v_pk_fma_f32 v[54:55], v[74:75], s[24:25], v[54:55] op_sel_hi:[1,0,1]
	v_pk_fma_f32 v[52:53], v[72:73], s[24:25], v[52:53] op_sel_hi:[1,0,1]
	v_pk_fma_f32 v[50:51], v[78:79], s[24:25], v[50:51] op_sel_hi:[1,0,1]
	v_lshlrev_b32_e32 v72, 16, v188
	v_and_b32_e32 v73, 0xffff0000, v188
	v_lshlrev_b32_e32 v74, 16, v189
	v_and_b32_e32 v75, 0xffff0000, v189
	v_lshlrev_b32_e32 v78, 16, v191
	v_and_b32_e32 v79, 0xffff0000, v191
	v_pk_fma_f32 v[60:61], v[64:65], s[24:25], v[60:61] op_sel_hi:[1,0,1]
	v_add_u32_e32 v64, s0, v144
	v_pk_fma_f32 v[112:113], v[142:143], s[24:25], v[112:113] op_sel_hi:[1,0,1]
	v_pk_fma_f32 v[142:143], v[74:75], s[24:25], v[70:71] op_sel_hi:[1,0,1]
	v_pk_fma_f32 v[140:141], v[72:73], s[24:25], v[68:69] op_sel_hi:[1,0,1]
	v_pk_fma_f32 v[138:139], v[78:79], s[24:25], v[66:67] op_sel_hi:[1,0,1]
	v_lshlrev_b32_e32 v66, 16, v193
	v_and_b32_e32 v67, 0xffff0000, v193
	v_lshlrev_b32_e32 v68, 16, v194
	v_and_b32_e32 v69, 0xffff0000, v194
	v_lshlrev_b32_e32 v70, 16, v195
	v_and_b32_e32 v71, 0xffff0000, v195
	v_ashrrev_i32_e32 v65, 31, v64
	v_pk_fma_f32 v[62:63], v[66:67], s[24:25], v[62:63] op_sel_hi:[1,0,1]
	v_pk_fma_f32 v[58:59], v[70:71], s[24:25], v[58:59] op_sel_hi:[1,0,1]
	v_pk_fma_f32 v[56:57], v[68:69], s[24:25], v[56:57] op_sel_hi:[1,0,1]
	v_lshlrev_b64 v[64:65], 2, v[64:65]
	v_lshl_add_u64 v[68:69], s[16:17], 0, v[64:65]
	v_lshl_add_u64 v[76:77], s[18:19], 0, v[64:65]
	global_load_dwordx4 v[144:147], v[68:69], off offset:16
	global_load_dwordx4 v[152:155], v[68:69], off
	global_load_dwordx4 v[148:151], v[76:77], off offset:16
	global_load_dwordx4 v[156:159], v[76:77], off
	global_load_dwordx4 v[64:67], v[68:69], off offset:528
	global_load_dwordx4 v[72:75], v[68:69], off offset:512
	s_nop 0
	global_load_dwordx4 v[68:71], v[76:77], off offset:528
	s_nop 0
	global_load_dwordx4 v[76:79], v[76:77], off offset:512
	v_pk_add_f32 v[188:189], v[104:105], v[96:97]
	v_pk_add_f32 v[190:191], v[30:31], v[18:19]
	v_pk_add_f32 v[192:193], v[28:29], v[16:17]
	v_pk_add_f32 v[174:175], v[174:175], v[190:191]
	v_pk_add_f32 v[188:189], v[188:189], v[192:193]
	v_add_f32_e32 v174, v174, v175
	v_add_f32_e32 v188, v188, v189
	v_add_f32_e32 v174, v188, v174
	v_mov_b32_e32 v175, v174
	s_nop 1
	v_permlane16_swap_b32_e32 v174, v175
	v_add_f32_e32 v174, v174, v175
	v_mov_b32_e32 v175, v174
	s_nop 1
	v_permlane32_swap_b32_e32 v174, v175
	v_add_f32_e32 v174, v174, v175
	v_fmamk_f32 v193, v174, 0xbc800000, v97
	v_fmamk_f32 v192, v174, 0xbc800000, v96
	v_fmamk_f32 v195, v174, 0xbc800000, v99
	v_fmamk_f32 v194, v174, 0xbc800000, v98
	v_fmamk_f32 v189, v174, 0xbc800000, v107
	v_fmamk_f32 v188, v174, 0xbc800000, v106
	v_fmamk_f32 v191, v174, 0xbc800000, v105
	v_fmamk_f32 v190, v174, 0xbc800000, v104
	v_fmamk_f32 v201, v174, 0xbc800000, v17
	v_fmamk_f32 v200, v174, 0xbc800000, v16
	v_fmamk_f32 v203, v174, 0xbc800000, v19
	v_fmamk_f32 v202, v174, 0xbc800000, v18
	v_pk_mul_f32 v[194:195], v[194:195], v[194:195]
	v_pk_mul_f32 v[192:193], v[192:193], v[192:193]
	v_fmamk_f32 v197, v174, 0xbc800000, v31
	v_fmamk_f32 v196, v174, 0xbc800000, v30
	v_fmamk_f32 v199, v174, 0xbc800000, v29
	v_fmamk_f32 v198, v174, 0xbc800000, v28
	v_pk_fma_f32 v[190:191], v[190:191], v[190:191], v[192:193]
	v_pk_fma_f32 v[188:189], v[188:189], v[188:189], v[194:195]
	v_pk_mul_f32 v[192:193], v[202:203], v[202:203]
	v_pk_mul_f32 v[194:195], v[200:201], v[200:201]
	v_pk_fma_f32 v[192:193], v[196:197], v[196:197], v[192:193]
	v_pk_fma_f32 v[194:195], v[198:199], v[198:199], v[194:195]
	v_pk_add_f32 v[188:189], v[188:189], v[192:193]
	v_pk_add_f32 v[190:191], v[190:191], v[194:195]
	v_add_f32_e32 v188, v188, v189
	v_add_f32_e32 v175, v190, v191
	v_add_f32_e32 v175, v175, v188
	v_mov_b32_e32 v188, v175
	s_nop 1
	v_permlane16_swap_b32_e32 v175, v188
	s_lshl_b32 s0, s6, 3
	v_add_f32_e32 v175, v175, v188
	s_add_i32 s9, s0, 0
	v_mov_b32_e32 v188, v175
	s_add_i32 s9, s9, 0x21000
	s_nop 0
	v_permlane32_swap_b32_e32 v175, v188
	s_and_saveexec_b64 s[0:1], vcc
	s_cbranch_execz .LBB0_2777
	s_lshl_b32 s13, s7, 11
	s_add_i32 s13, s9, s13
	v_mul_f32_e32 v174, 0x3c800000, v174
	v_add_f32_e32 v175, v175, v188
	v_lshl_add_u32 v188, v186, 5, s13
	ds_write_b64 v188, v[174:175]

.LBB0_2969:
	v_mov_b32_e32 v177, v183
	s_mov_b32 s2, s45
	v_mov_b32_e32 v176, v184
	s_mov_b32 s3, s66
	s_lshl_b32 s0, s8, 2
	s_ashr_i32 s1, s3, 1
	s_lshl_b32 s25, s2, 6
	s_add_i32 s0, s1, s0
	s_lshl_b32 s4, s31, 8
	s_ashr_i32 s1, s0, 31
	s_add_i32 s5, s25, s4
	s_lshl_b32 s34, s3, 5
	v_add_u32_e32 v128, s5, v177
	s_lshl_b64 s[0:1], s[0:1], 22
	v_ashrrev_i32_e32 v129, 31, v128
	s_add_u32 s0, s58, s0
	v_lshlrev_b64 v[128:129], 7, v[128:129]
	s_addc_u32 s1, s59, s1
	v_lshl_add_u64 v[128:129], s[0:1], 0, v[128:129]
	s_lshl_b32 s0, s3, 6
	v_lshlrev_b32_e32 v148, 3, v176
	s_and_b32 s6, s0, 64
	v_ashrrev_i32_e32 v149, 31, v148
	v_lshl_add_u64 v[128:129], v[128:129], 0, s[6:7]
	v_lshl_add_u64 v[128:129], v[148:149], 1, v[128:129]
	v_add_co_u32_e32 v146, vcc, s71, v128
	global_load_dwordx4 v[130:133], v[128:129], off nt
	global_load_dwordx4 v[134:137], v[128:129], off offset:2048 nt
	v_addc_co_u32_e32 v147, vcc, 0, v129, vcc
	v_add_co_u32_e32 v142, vcc, s33, v128
	global_load_dwordx4 v[138:141], v[146:147], off offset:-4096 nt
	s_nop 0
	v_addc_co_u32_e32 v143, vcc, 0, v129, vcc
	global_load_dwordx4 v[142:145], v[142:143], off offset:2048 nt
	v_add_co_u32_e32 v158, vcc, s70, v128
	global_load_dwordx4 v[154:157], v[146:147], off nt
	s_nop 0
	v_addc_co_u32_e32 v159, vcc, 0, v129, vcc
	global_load_dwordx4 v[150:153], v[158:159], off nt
	global_load_dwordx4 v[178:181], v[158:159], off offset:2048 nt
	global_load_dwordx4 v[192:195], v[146:147], off offset:2048 nt
	v_pk_mul_f32 v[50:51], v[50:51], 0.5 op_sel_hi:[1,0]
	v_pk_mul_f32 v[48:49], v[48:49], 0.5 op_sel_hi:[1,0]
	v_pk_mul_f32 v[174:175], v[46:47], 0.5 op_sel_hi:[1,0]
	v_pk_mul_f32 v[196:197], v[44:45], 0.5 op_sel_hi:[1,0]
	v_pk_mul_f32 v[198:199], v[42:43], 0.5 op_sel_hi:[1,0]
	v_pk_mul_f32 v[200:201], v[40:41], 0.5 op_sel_hi:[1,0]
	v_pk_mul_f32 v[14:15], v[14:15], 0.5 op_sel_hi:[1,0]
	v_pk_mul_f32 v[12:13], v[12:13], 0.5 op_sel_hi:[1,0]
	v_pk_mul_f32 v[54:55], v[54:55], 0.5 op_sel_hi:[1,0]
	v_pk_mul_f32 v[52:53], v[52:53], 0.5 op_sel_hi:[1,0]
	v_pk_mul_f32 v[2:3], v[2:3], 0.5 op_sel_hi:[1,0]
	v_pk_mul_f32 v[0:1], v[0:1], 0.5 op_sel_hi:[1,0]
	s_lshl_b32 s0, s8, 8
	s_add_i32 s0, s34, s0
	s_waitcnt vmcnt(0)
	v_lshlrev_b32_e32 v40, 16, v130
	v_and_b32_e32 v41, 0xffff0000, v130
	v_lshlrev_b32_e32 v42, 16, v131
	v_and_b32_e32 v43, 0xffff0000, v131
	v_lshlrev_b32_e32 v44, 16, v132
	v_and_b32_e32 v45, 0xffff0000, v132
	v_lshlrev_b32_e32 v46, 16, v133
	v_and_b32_e32 v47, 0xffff0000, v133
	v_lshlrev_b32_e32 v130, 16, v134
	v_and_b32_e32 v131, 0xffff0000, v134
	v_lshlrev_b32_e32 v132, 16, v135
	v_and_b32_e32 v133, 0xffff0000, v135
	v_lshlrev_b32_e32 v134, 16, v136
	v_and_b32_e32 v135, 0xffff0000, v136
	v_lshlrev_b32_e32 v136, 16, v137
	v_and_b32_e32 v137, 0xffff0000, v137
	v_pk_fma_f32 v[50:51], v[46:47], s[22:23], v[50:51] op_sel_hi:[1,0,1]
	v_pk_fma_f32 v[48:49], v[44:45], s[22:23], v[48:49] op_sel_hi:[1,0,1]
	v_pk_fma_f32 v[46:47], v[132:133], s[22:23], v[14:15] op_sel_hi:[1,0,1]
	v_pk_fma_f32 v[44:45], v[130:131], s[22:23], v[12:13] op_sel_hi:[1,0,1]
	v_lshlrev_b32_e32 v130, 16, v142
	v_and_b32_e32 v131, 0xffff0000, v142
	v_lshlrev_b32_e32 v132, 16, v143
	v_and_b32_e32 v133, 0xffff0000, v143
	v_pk_fma_f32 v[54:55], v[42:43], s[22:23], v[54:55] op_sel_hi:[1,0,1]
	v_pk_fma_f32 v[52:53], v[40:41], s[22:23], v[52:53] op_sel_hi:[1,0,1]
	v_pk_fma_f32 v[42:43], v[136:137], s[22:23], v[2:3] op_sel_hi:[1,0,1]
	v_pk_fma_f32 v[40:41], v[134:135], s[22:23], v[0:1] op_sel_hi:[1,0,1]
	v_lshlrev_b32_e32 v134, 16, v144
	v_and_b32_e32 v135, 0xffff0000, v144
	v_lshlrev_b32_e32 v136, 16, v145
	v_and_b32_e32 v137, 0xffff0000, v145
	v_pk_mul_f32 v[130:131], v[130:131], s[22:23] op_sel_hi:[1,0]
	v_pk_mul_f32 v[132:133], v[132:133], s[22:23] op_sel_hi:[1,0]
	v_pk_fma_f32 v[4:5], v[4:5], 0.5, v[130:131] op_sel_hi:[1,0,1]
	v_pk_fma_f32 v[6:7], v[6:7], 0.5, v[132:133] op_sel_hi:[1,0,1]
	v_pk_mul_f32 v[130:131], v[134:135], s[22:23] op_sel_hi:[1,0]
	v_pk_mul_f32 v[132:133], v[136:137], s[22:23] op_sel_hi:[1,0]
	v_pk_fma_f32 v[8:9], v[8:9], 0.5, v[130:131] op_sel_hi:[1,0,1]
	v_pk_fma_f32 v[10:11], v[10:11], 0.5, v[132:133] op_sel_hi:[1,0,1]
	v_lshlrev_b32_e32 v130, 16, v150
	v_and_b32_e32 v131, 0xffff0000, v150
	v_lshlrev_b32_e32 v132, 16, v151
	v_and_b32_e32 v133, 0xffff0000, v151
	v_lshlrev_b32_e32 v134, 16, v152
	v_and_b32_e32 v135, 0xffff0000, v152
	v_lshlrev_b32_e32 v136, 16, v153
	v_and_b32_e32 v137, 0xffff0000, v153
	v_pk_mul_f32 v[130:131], v[130:131], s[22:23] op_sel_hi:[1,0]
	v_pk_mul_f32 v[132:133], v[132:133], s[22:23] op_sel_hi:[1,0]
	v_pk_fma_f32 v[64:65], v[64:65], 0.5, v[130:131] op_sel_hi:[1,0,1]
	v_pk_fma_f32 v[66:67], v[66:67], 0.5, v[132:133] op_sel_hi:[1,0,1]
	v_pk_mul_f32 v[130:131], v[134:135], s[22:23] op_sel_hi:[1,0]
	v_pk_mul_f32 v[132:133], v[136:137], s[22:23] op_sel_hi:[1,0]
	v_pk_fma_f32 v[68:69], v[68:69], 0.5, v[130:131] op_sel_hi:[1,0,1]
	v_pk_fma_f32 v[70:71], v[70:71], 0.5, v[132:133] op_sel_hi:[1,0,1]
	v_lshlrev_b32_e32 v130, 16, v154
	v_and_b32_e32 v131, 0xffff0000, v154
	v_lshlrev_b32_e32 v132, 16, v155
	v_and_b32_e32 v133, 0xffff0000, v155
	v_lshlrev_b32_e32 v134, 16, v156
	v_and_b32_e32 v135, 0xffff0000, v156
	v_lshlrev_b32_e32 v136, 16, v157
	v_and_b32_e32 v137, 0xffff0000, v157
	v_pk_mul_f32 v[130:131], v[130:131], s[22:23] op_sel_hi:[1,0]
	v_pk_mul_f32 v[132:133], v[132:133], s[22:23] op_sel_hi:[1,0]
	v_pk_fma_f32 v[16:17], v[16:17], 0.5, v[130:131] op_sel_hi:[1,0,1]
	v_pk_fma_f32 v[18:19], v[18:19], 0.5, v[132:133] op_sel_hi:[1,0,1]
	v_pk_mul_f32 v[130:131], v[134:135], s[22:23] op_sel_hi:[1,0]
	v_pk_mul_f32 v[132:133], v[136:137], s[22:23] op_sel_hi:[1,0]
	v_pk_fma_f32 v[20:21], v[20:21], 0.5, v[130:131] op_sel_hi:[1,0,1]
	v_pk_fma_f32 v[22:23], v[22:23], 0.5, v[132:133] op_sel_hi:[1,0,1]
	v_lshlrev_b32_e32 v130, 16, v178
	v_and_b32_e32 v131, 0xffff0000, v178
	v_lshlrev_b32_e32 v132, 16, v179
	v_and_b32_e32 v133, 0xffff0000, v179
	v_lshlrev_b32_e32 v134, 16, v180
	v_and_b32_e32 v135, 0xffff0000, v180
	v_lshlrev_b32_e32 v136, 16, v181
	v_and_b32_e32 v137, 0xffff0000, v181
	v_pk_mul_f32 v[130:131], v[130:131], s[22:23] op_sel_hi:[1,0]
	v_pk_mul_f32 v[132:133], v[132:133], s[22:23] op_sel_hi:[1,0]
	v_pk_fma_f32 v[80:81], v[80:81], 0.5, v[130:131] op_sel_hi:[1,0,1]
	v_pk_fma_f32 v[82:83], v[82:83], 0.5, v[132:133] op_sel_hi:[1,0,1]
	v_pk_mul_f32 v[130:131], v[134:135], s[22:23] op_sel_hi:[1,0]
	v_pk_mul_f32 v[132:133], v[136:137], s[22:23] op_sel_hi:[1,0]
	v_pk_fma_f32 v[84:85], v[84:85], 0.5, v[130:131] op_sel_hi:[1,0,1]
	v_pk_fma_f32 v[86:87], v[86:87], 0.5, v[132:133] op_sel_hi:[1,0,1]
	v_lshlrev_b32_e32 v130, 16, v192
	v_and_b32_e32 v131, 0xffff0000, v192
	v_lshlrev_b32_e32 v132, 16, v193
	v_and_b32_e32 v133, 0xffff0000, v193
	v_lshlrev_b32_e32 v134, 16, v194
	v_and_b32_e32 v135, 0xffff0000, v194
	v_lshlrev_b32_e32 v136, 16, v195
	v_and_b32_e32 v137, 0xffff0000, v195
	v_pk_mul_f32 v[130:131], v[130:131], s[22:23] op_sel_hi:[1,0]
	v_pk_mul_f32 v[132:133], v[132:133], s[22:23] op_sel_hi:[1,0]
	v_lshlrev_b32_e32 v146, 16, v138
	v_and_b32_e32 v147, 0xffff0000, v138
	v_lshlrev_b32_e32 v138, 16, v139
	v_and_b32_e32 v139, 0xffff0000, v139
	v_lshlrev_b32_e32 v158, 16, v140
	v_and_b32_e32 v159, 0xffff0000, v140
	v_lshlrev_b32_e32 v140, 16, v141
	v_and_b32_e32 v141, 0xffff0000, v141
	v_pk_fma_f32 v[26:27], v[26:27], 0.5, v[132:133] op_sel_hi:[1,0,1]
	v_pk_fma_f32 v[24:25], v[24:25], 0.5, v[130:131] op_sel_hi:[1,0,1]
	v_pk_mul_f32 v[130:131], v[134:135], s[22:23] op_sel_hi:[1,0]
	v_pk_mul_f32 v[132:133], v[136:137], s[22:23] op_sel_hi:[1,0]
	v_pk_fma_f32 v[14:15], v[138:139], s[22:23], v[174:175] op_sel_hi:[1,0,1]
	v_pk_fma_f32 v[12:13], v[146:147], s[22:23], v[196:197] op_sel_hi:[1,0,1]
	v_pk_fma_f32 v[2:3], v[140:141], s[22:23], v[198:199] op_sel_hi:[1,0,1]
	v_pk_fma_f32 v[0:1], v[158:159], s[22:23], v[200:201] op_sel_hi:[1,0,1]
	v_pk_fma_f32 v[30:31], v[30:31], 0.5, v[132:133] op_sel_hi:[1,0,1]
	v_pk_fma_f32 v[28:29], v[28:29], 0.5, v[130:131] op_sel_hi:[1,0,1]
	v_add_co_u32_e32 v142, vcc, s73, v128
	s_nop 1
	v_addc_co_u32_e32 v143, vcc, 0, v129, vcc
	global_load_dwordx4 v[130:133], v[142:143], off offset:-4096 nt
	v_add_co_u32_e32 v144, vcc, s74, v128
	v_pk_add_f32 v[174:175], v[54:55], v[50:51]
	s_nop 0
	v_addc_co_u32_e32 v145, vcc, 0, v129, vcc
	global_load_dwordx4 v[134:137], v[144:145], off offset:-4096 nt
	v_add_co_u32_e32 v138, vcc, s56, v128
	s_nop 1
	v_addc_co_u32_e32 v139, vcc, 0, v129, vcc
	global_load_dwordx4 v[138:141], v[138:139], off offset:2048 nt
	v_add_co_u32_e32 v128, vcc, s72, v128
	s_nop 1
	v_addc_co_u32_e32 v129, vcc, 0, v129, vcc
	global_load_dwordx4 v[150:153], v[128:129], off offset:2048 nt
	global_load_dwordx4 v[154:157], v[142:143], off nt
	global_load_dwordx4 v[178:181], v[142:143], off offset:2048 nt
	global_load_dwordx4 v[192:195], v[144:145], off nt
	s_nop 0
	global_load_dwordx4 v[144:147], v[144:145], off offset:2048 nt
	v_cmp_eq_u32_e32 vcc, 0, v176
	s_waitcnt vmcnt(7)
	v_lshlrev_b32_e32 v128, 16, v130
	v_and_b32_e32 v129, 0xffff0000, v130
	v_lshlrev_b32_e32 v142, 16, v132
	v_and_b32_e32 v143, 0xffff0000, v132
	v_pk_mul_f32 v[128:129], v[128:129], s[22:23] op_sel_hi:[1,0]
	v_lshlrev_b32_e32 v130, 16, v131
	v_and_b32_e32 v131, 0xffff0000, v131
	v_pk_fma_f32 v[104:105], v[104:105], 0.5, v[128:129] op_sel_hi:[1,0,1]
	v_pk_mul_f32 v[128:129], v[142:143], s[22:23] op_sel_hi:[1,0]
	v_lshlrev_b32_e32 v132, 16, v133
	v_and_b32_e32 v133, 0xffff0000, v133
	v_pk_mul_f32 v[130:131], v[130:131], s[22:23] op_sel_hi:[1,0]
	v_pk_fma_f32 v[108:109], v[108:109], 0.5, v[128:129] op_sel_hi:[1,0,1]
	s_waitcnt vmcnt(6)
	v_lshlrev_b32_e32 v128, 16, v134
	v_and_b32_e32 v129, 0xffff0000, v134
	v_pk_fma_f32 v[106:107], v[106:107], 0.5, v[130:131] op_sel_hi:[1,0,1]
	v_pk_mul_f32 v[130:131], v[132:133], s[22:23] op_sel_hi:[1,0]
	v_lshlrev_b32_e32 v132, 16, v136
	v_and_b32_e32 v133, 0xffff0000, v136
	v_pk_mul_f32 v[128:129], v[128:129], s[22:23] op_sel_hi:[1,0]
	v_pk_fma_f32 v[110:111], v[110:111], 0.5, v[130:131] op_sel_hi:[1,0,1]
	v_lshlrev_b32_e32 v130, 16, v135
	v_and_b32_e32 v131, 0xffff0000, v135
	v_pk_fma_f32 v[32:33], v[32:33], 0.5, v[128:129] op_sel_hi:[1,0,1]
	v_pk_mul_f32 v[128:129], v[132:133], s[22:23] op_sel_hi:[1,0]
	v_lshlrev_b32_e32 v134, 16, v137
	v_and_b32_e32 v135, 0xffff0000, v137
	v_pk_mul_f32 v[130:131], v[130:131], s[22:23] op_sel_hi:[1,0]
	v_pk_fma_f32 v[36:37], v[36:37], 0.5, v[128:129] op_sel_hi:[1,0,1]
	s_waitcnt vmcnt(5)
	v_lshlrev_b32_e32 v128, 16, v138
	v_and_b32_e32 v129, 0xffff0000, v138
	v_pk_fma_f32 v[34:35], v[34:35], 0.5, v[130:131] op_sel_hi:[1,0,1]
	v_pk_mul_f32 v[130:131], v[134:135], s[22:23] op_sel_hi:[1,0]
	v_lshlrev_b32_e32 v132, 16, v140
	v_and_b32_e32 v133, 0xffff0000, v140
	v_pk_mul_f32 v[128:129], v[128:129], s[22:23] op_sel_hi:[1,0]
	v_pk_fma_f32 v[38:39], v[38:39], 0.5, v[130:131] op_sel_hi:[1,0,1]
	v_lshlrev_b32_e32 v130, 16, v139
	v_and_b32_e32 v131, 0xffff0000, v139
	v_pk_fma_f32 v[120:121], v[120:121], 0.5, v[128:129] op_sel_hi:[1,0,1]
	v_pk_mul_f32 v[128:129], v[132:133], s[22:23] op_sel_hi:[1,0]
	v_lshlrev_b32_e32 v134, 16, v141
	v_and_b32_e32 v135, 0xffff0000, v141
	v_pk_mul_f32 v[130:131], v[130:131], s[22:23] op_sel_hi:[1,0]
	v_pk_fma_f32 v[124:125], v[124:125], 0.5, v[128:129] op_sel_hi:[1,0,1]
	s_waitcnt vmcnt(4)
	v_lshlrev_b32_e32 v128, 16, v150
	v_and_b32_e32 v129, 0xffff0000, v150
	v_pk_fma_f32 v[122:123], v[122:123], 0.5, v[130:131] op_sel_hi:[1,0,1]
	v_pk_mul_f32 v[130:131], v[134:135], s[22:23] op_sel_hi:[1,0]
	v_lshlrev_b32_e32 v132, 16, v152
	v_and_b32_e32 v133, 0xffff0000, v152
	v_pk_mul_f32 v[128:129], v[128:129], s[22:23] op_sel_hi:[1,0]
	v_pk_fma_f32 v[126:127], v[126:127], 0.5, v[130:131] op_sel_hi:[1,0,1]
	v_lshlrev_b32_e32 v130, 16, v151
	v_and_b32_e32 v131, 0xffff0000, v151
	v_pk_fma_f32 v[56:57], v[56:57], 0.5, v[128:129] op_sel_hi:[1,0,1]
	v_pk_mul_f32 v[128:129], v[132:133], s[22:23] op_sel_hi:[1,0]
	v_lshlrev_b32_e32 v134, 16, v153
	v_and_b32_e32 v135, 0xffff0000, v153
	v_pk_mul_f32 v[130:131], v[130:131], s[22:23] op_sel_hi:[1,0]
	v_pk_fma_f32 v[60:61], v[60:61], 0.5, v[128:129] op_sel_hi:[1,0,1]
	s_waitcnt vmcnt(3)
	v_lshlrev_b32_e32 v128, 16, v154
	v_and_b32_e32 v129, 0xffff0000, v154
	v_pk_fma_f32 v[58:59], v[58:59], 0.5, v[130:131] op_sel_hi:[1,0,1]
	v_pk_mul_f32 v[130:131], v[134:135], s[22:23] op_sel_hi:[1,0]
	v_lshlrev_b32_e32 v132, 16, v156
	v_and_b32_e32 v133, 0xffff0000, v156
	v_pk_mul_f32 v[128:129], v[128:129], s[22:23] op_sel_hi:[1,0]
	v_pk_fma_f32 v[62:63], v[62:63], 0.5, v[130:131] op_sel_hi:[1,0,1]
	v_lshlrev_b32_e32 v130, 16, v155
	v_and_b32_e32 v131, 0xffff0000, v155
	v_pk_fma_f32 v[128:129], v[116:117], 0.5, v[128:129] op_sel_hi:[1,0,1]
	v_pk_mul_f32 v[116:117], v[132:133], s[22:23] op_sel_hi:[1,0]
	v_lshlrev_b32_e32 v134, 16, v157
	v_and_b32_e32 v135, 0xffff0000, v157
	v_pk_mul_f32 v[130:131], v[130:131], s[22:23] op_sel_hi:[1,0]
	v_pk_fma_f32 v[132:133], v[112:113], 0.5, v[116:117] op_sel_hi:[1,0,1]
	s_waitcnt vmcnt(1)
	v_lshlrev_b32_e32 v112, 16, v192
	v_and_b32_e32 v113, 0xffff0000, v192
	v_pk_fma_f32 v[130:131], v[118:119], 0.5, v[130:131] op_sel_hi:[1,0,1]
	v_pk_mul_f32 v[118:119], v[134:135], s[22:23] op_sel_hi:[1,0]
	v_lshlrev_b32_e32 v116, 16, v194
	v_and_b32_e32 v117, 0xffff0000, v194
	v_pk_mul_f32 v[112:113], v[112:113], s[22:23] op_sel_hi:[1,0]
	v_pk_fma_f32 v[134:135], v[114:115], 0.5, v[118:119] op_sel_hi:[1,0,1]
	v_lshlrev_b32_e32 v114, 16, v193
	v_and_b32_e32 v115, 0xffff0000, v193
	v_pk_fma_f32 v[72:73], v[72:73], 0.5, v[112:113] op_sel_hi:[1,0,1]
	v_pk_mul_f32 v[112:113], v[116:117], s[22:23] op_sel_hi:[1,0]
	v_lshlrev_b32_e32 v118, 16, v195
	v_and_b32_e32 v119, 0xffff0000, v195
	v_pk_mul_f32 v[114:115], v[114:115], s[22:23] op_sel_hi:[1,0]
	v_pk_fma_f32 v[76:77], v[76:77], 0.5, v[112:113] op_sel_hi:[1,0,1]
	v_lshlrev_b32_e32 v112, 16, v178
	v_and_b32_e32 v113, 0xffff0000, v178
	v_pk_fma_f32 v[74:75], v[74:75], 0.5, v[114:115] op_sel_hi:[1,0,1]
	v_pk_mul_f32 v[114:115], v[118:119], s[22:23] op_sel_hi:[1,0]
	v_lshlrev_b32_e32 v116, 16, v180
	v_and_b32_e32 v117, 0xffff0000, v180
	v_pk_mul_f32 v[112:113], v[112:113], s[22:23] op_sel_hi:[1,0]
	v_pk_fma_f32 v[78:79], v[78:79], 0.5, v[114:115] op_sel_hi:[1,0,1]
	v_lshlrev_b32_e32 v114, 16, v179
	v_and_b32_e32 v115, 0xffff0000, v179
	v_pk_fma_f32 v[136:137], v[100:101], 0.5, v[112:113] op_sel_hi:[1,0,1]
	v_pk_mul_f32 v[100:101], v[116:117], s[22:23] op_sel_hi:[1,0]
	v_lshlrev_b32_e32 v118, 16, v181
	v_and_b32_e32 v119, 0xffff0000, v181
	v_pk_mul_f32 v[114:115], v[114:115], s[22:23] op_sel_hi:[1,0]
	v_pk_fma_f32 v[140:141], v[96:97], 0.5, v[100:101] op_sel_hi:[1,0,1]
	s_waitcnt vmcnt(0)
	v_lshlrev_b32_e32 v96, 16, v144
	v_and_b32_e32 v97, 0xffff0000, v144
	v_pk_fma_f32 v[138:139], v[102:103], 0.5, v[114:115] op_sel_hi:[1,0,1]
	v_pk_mul_f32 v[102:103], v[118:119], s[22:23] op_sel_hi:[1,0]
	v_lshlrev_b32_e32 v100, 16, v146
	v_and_b32_e32 v101, 0xffff0000, v146
	v_pk_mul_f32 v[96:97], v[96:97], s[22:23] op_sel_hi:[1,0]
	v_pk_fma_f32 v[142:143], v[98:99], 0.5, v[102:103] op_sel_hi:[1,0,1]
	v_lshlrev_b32_e32 v98, 16, v145
	v_and_b32_e32 v99, 0xffff0000, v145
	v_pk_fma_f32 v[92:93], v[92:93], 0.5, v[96:97] op_sel_hi:[1,0,1]
	v_pk_mul_f32 v[96:97], v[100:101], s[22:23] op_sel_hi:[1,0]
	v_lshlrev_b32_e32 v102, 16, v147
	v_and_b32_e32 v103, 0xffff0000, v147
	v_pk_mul_f32 v[98:99], v[98:99], s[22:23] op_sel_hi:[1,0]
	v_pk_fma_f32 v[88:89], v[88:89], 0.5, v[96:97] op_sel_hi:[1,0,1]
	v_add_u32_e32 v96, s0, v148
	v_pk_fma_f32 v[94:95], v[94:95], 0.5, v[98:99] op_sel_hi:[1,0,1]
	v_pk_mul_f32 v[98:99], v[102:103], s[22:23] op_sel_hi:[1,0]
	v_ashrrev_i32_e32 v97, 31, v96
	v_pk_fma_f32 v[90:91], v[90:91], 0.5, v[98:99] op_sel_hi:[1,0,1]
	v_lshlrev_b64 v[96:97], 2, v[96:97]
	v_lshl_add_u64 v[100:101], s[14:15], 0, v[96:97]
	v_lshl_add_u64 v[116:117], s[16:17], 0, v[96:97]
	global_load_dwordx4 v[144:147], v[100:101], off offset:16
	global_load_dwordx4 v[152:155], v[100:101], off
	global_load_dwordx4 v[148:151], v[116:117], off offset:16
	global_load_dwordx4 v[156:159], v[116:117], off
	global_load_dwordx4 v[96:99], v[100:101], off offset:528
	global_load_dwordx4 v[112:115], v[100:101], off offset:512
	s_nop 0
	global_load_dwordx4 v[100:103], v[116:117], off offset:528
	s_nop 0
	global_load_dwordx4 v[116:119], v[116:117], off offset:512
	v_pk_add_f32 v[178:179], v[52:53], v[48:49]
	v_pk_add_f32 v[180:181], v[14:15], v[2:3]
	v_pk_add_f32 v[192:193], v[12:13], v[0:1]
	v_pk_add_f32 v[174:175], v[174:175], v[180:181]
	v_pk_add_f32 v[178:179], v[178:179], v[192:193]
	v_add_f32_e32 v174, v174, v175
	v_add_f32_e32 v178, v178, v179
	v_add_f32_e32 v174, v178, v174
	v_mov_b32_e32 v175, v174
	s_nop 1
	v_permlane16_swap_b32_e32 v174, v175
	v_add_f32_e32 v174, v174, v175
	v_mov_b32_e32 v175, v174
	s_nop 1
	v_permlane32_swap_b32_e32 v174, v175
	v_add_f32_e32 v174, v174, v175
	v_fmamk_f32 v193, v174, 0xbc800000, v49
	v_fmamk_f32 v192, v174, 0xbc800000, v48
	v_fmamk_f32 v195, v174, 0xbc800000, v51
	v_fmamk_f32 v194, v174, 0xbc800000, v50
	v_fmamk_f32 v179, v174, 0xbc800000, v55
	v_fmamk_f32 v178, v174, 0xbc800000, v54
	v_fmamk_f32 v181, v174, 0xbc800000, v53
	v_fmamk_f32 v180, v174, 0xbc800000, v52
	v_fmamk_f32 v201, v174, 0xbc800000, v1
	v_fmamk_f32 v200, v174, 0xbc800000, v0
	v_fmamk_f32 v203, v174, 0xbc800000, v3
	v_fmamk_f32 v202, v174, 0xbc800000, v2
	v_pk_mul_f32 v[194:195], v[194:195], v[194:195]
	v_pk_mul_f32 v[192:193], v[192:193], v[192:193]
	v_fmamk_f32 v197, v174, 0xbc800000, v15
	v_fmamk_f32 v196, v174, 0xbc800000, v14
	v_fmamk_f32 v199, v174, 0xbc800000, v13
	v_fmamk_f32 v198, v174, 0xbc800000, v12
	v_pk_fma_f32 v[180:181], v[180:181], v[180:181], v[192:193]
	v_pk_fma_f32 v[178:179], v[178:179], v[178:179], v[194:195]
	v_pk_mul_f32 v[192:193], v[202:203], v[202:203]
	v_pk_mul_f32 v[194:195], v[200:201], v[200:201]
	v_pk_fma_f32 v[192:193], v[196:197], v[196:197], v[192:193]
	v_pk_fma_f32 v[194:195], v[198:199], v[198:199], v[194:195]
	v_pk_add_f32 v[178:179], v[178:179], v[192:193]
	v_pk_add_f32 v[180:181], v[180:181], v[194:195]
	v_add_f32_e32 v178, v178, v179
	v_add_f32_e32 v175, v180, v181
	v_add_f32_e32 v175, v175, v178
	v_mov_b32_e32 v178, v175
	s_nop 1
	v_permlane16_swap_b32_e32 v175, v178
	s_lshl_b32 s0, s3, 3
	v_add_f32_e32 v175, v175, v178
	s_add_i32 s5, s0, 0
	v_mov_b32_e32 v178, v175
	s_add_i32 s5, s5, 0x21000
	s_nop 0
	v_permlane32_swap_b32_e32 v175, v178
	s_and_saveexec_b64 s[0:1], vcc
	s_cbranch_execz .LBB0_2971
	s_lshl_b32 s6, s2, 11
	s_add_i32 s6, s5, s6
	v_mul_f32_e32 v174, 0x3c800000, v174
	v_lshl_add_u32 v179, v177, 5, s6
	v_add_f32_e32 v175, v175, v178
	ds_write_b64 v179, v[174:175]
